# kept configuration (10 of 14 barriers XCD-local) + priority see-saw along the GEMM4 epilogue
# baseline (speedup 1.0000x reference)
; __device__ __forceinline__ unsigned cvt_pk_bf16(float lo, float hi) { unsigned r; asm volatile("v_cvt_pk_bf16_f32 %0, %1, %2" : "=v"(r) : "v"(lo), "v"(hi)); return r; }
; __device__ __forceinline__ float row_rs(const float* PS, int row, int fq) { return rsqrtf(PS[row] * (1.0f / 1024.0f) + 1e-6f); }
;     __device__ __forceinline__ void operator()(f32x4 (&acc)[2][2][4][2], const Unit& u, int wr, int wc, int fr, int fq) const {
;     ...
;         for (int ai = 0; ai < 2; ++ai)
; #pragma unroll
;             for (int m = 0; m < 4; ++m) { const float rs = row_rs(PS, row0 + ai * HALF + m * 16, fq);
; #pragma unroll
;                 for (int bj = 0; bj < 2; ++bj) { acc[ai][bj][m][0] *= rs; acc[ai][bj][m][1] *= rs; } }
;         if (fr < 2 || fr >= 14) {
; #pragma unroll
;             for (int ai = 0; ai < 2; ++ai)
; #pragma unroll
;                 for (int bj = 0; bj < 2; ++bj) { const f32x4 a0 = (fr < 2) ? acc[ai][bj][0][0] : acc[ai][bj][3][0], a1 = (fr < 2) ? acc[ai][bj][0][1] : acc[ai][bj][3][1];
;                     u32x4 w; w.x = cvt_pk_bf16(a0[0], a0[1]); w.y = cvt_pk_bf16(a0[2], a0[3]); w.z = cvt_pk_bf16(a1[0], a1[1]); w.w = cvt_pk_bf16(a1[2], a1[3]);
;                     *(u32x4*)(halo + ((size_t)((u.pm * 4 + ai * 2 + wr) * 4) + (fr < 2 ? fr : fr - 12)) * 5632 + bj * 2816 + f0) = w; } }
; #pragma unroll
;         for (int ai = 0; ai < 2; ++ai) {
;             unsigned pk[4][2][2];
; #pragma unroll
;             for (int n = 0; n < 2; ++n) {
;     ...
;                 const f32x4 wg0 = CQ4(0, 0), wg1 = CQ4(0, 1), wg2 = CQ4(0, 2), bg = CQ4(0, 3);
;                 const f32x4 wv0 = CQ4(1, 0), wv1 = CQ4(1, 1), wv2 = CQ4(1, 2), bv = CQ4(1, 3);
;     ...
;                 f32x4 pg1 = {0.f, 0.f, 0.f, 0.f}, pg2 = pg1, pv1 = pg1, pv2 = pg1;
; #pragma unroll
;                 for (int m = 0; m < 4; ++m) {
;                     const f32x4 zg = acc[ai][0][m][n], zv = acc[ai][1][m][n];
;                     f32x4 g1, g2, v1, v2;
; #pragma unroll
;                     for (int j = 0; j < 4; ++j) { g1[j] = dpp_shr1(pg1[j], zg[j]); g2[j] = dpp_shr2(pg2[j], zg[j]); v1[j] = dpp_shr1(pv1[j], zv[j]); v2[j] = dpp_shr2(pv2[j], zv[j]);
;                         pg1[j] = dpp_ror1(zg[j]); pg2[j] = dpp_ror2(zg[j]); pv1[j] = dpp_ror1(zv[j]); pv2[j] = dpp_ror2(zv[j]); }
;                     const f32x4 cg_ = bg + wg0 * g2 + wg1 * g1 + wg2 * zg, cv_ = bv + wv0 * v2 + wv1 * v1 + wv2 * zv;
.LBB0_40:
	s_or_b64 exec, exec, s[18:19]
	s_nop 0
	v_fmamk_f32 v144, v163, 0x3a800000, v196
	v_mul_f32_e32 v145, 0x4b800000, v144
	v_cmp_gt_f32_e32 vcc, s13, v144
	s_movk_i32 s22, 0x1600
	s_setprio 1
	v_or_b32_e32 v249, 16, v176
	v_cndmask_b32_e32 v144, v144, v145, vcc
	v_rsq_f32_e32 v144, v144
	v_or_b32_e32 v250, 32, v176
	v_or_b32_e32 v251, 48, v176
	v_add_u32_e32 v246, 0x80, v176
	v_mul_f32_e32 v145, 0x45800000, v144
	v_cndmask_b32_e32 v144, v144, v145, vcc
	v_pk_mul_f32 v[226:227], v[56:57], v[144:145] op_sel_hi:[1,0]
	v_fmamk_f32 v56, v162, 0x3a800000, v196
	v_mul_f32_e32 v57, 0x4b800000, v56
	v_cmp_gt_f32_e32 vcc, s13, v56
	v_pk_mul_f32 v[210:211], v[44:45], v[144:145] op_sel_hi:[1,0]
	v_pk_mul_f32 v[214:215], v[62:63], v[144:145] op_sel_hi:[1,0]
	v_cndmask_b32_e32 v56, v56, v57, vcc
	v_rsq_f32_e32 v56, v56
	v_lshlrev_b32_e32 v62, 16, v96
	v_and_b32_e32 v63, 0xffff0000, v96
	v_pk_mul_f32 v[230:231], v[66:67], v[144:145] op_sel_hi:[1,0]
	v_mul_f32_e32 v44, 0x45800000, v56
	v_cndmask_b32_e32 v44, v56, v44, vcc
	v_pk_mul_f32 v[202:203], v[36:37], v[44:45] op_sel_hi:[1,0]
	v_fmamk_f32 v36, v123, 0x3a800000, v196
	v_mul_f32_e32 v37, 0x4b800000, v36
	v_cmp_gt_f32_e32 vcc, s13, v36
	v_pk_mul_f32 v[206:207], v[50:51], v[44:45] op_sel_hi:[1,0]
	v_lshlrev_b32_e32 v50, 16, v84
	v_cndmask_b32_e32 v36, v36, v37, vcc
	v_rsq_f32_e32 v36, v36
	v_and_b32_e32 v51, 0xffff0000, v84
	v_pk_mul_f32 v[222:223], v[54:55], v[44:45] op_sel_hi:[1,0]
	v_pk_mul_f32 v[208:209], v[48:49], v[44:45] op_sel_hi:[1,0]
	v_mul_f32_e32 v37, 0x45800000, v36
	v_cndmask_b32_e32 v36, v36, v37, vcc
	v_pk_mul_f32 v[162:163], v[24:25], v[36:37] op_sel_hi:[1,0]
	v_fmamk_f32 v24, v122, 0x3a800000, v196
	v_mul_f32_e32 v25, 0x4b800000, v24
	v_cmp_gt_f32_e32 vcc, s13, v24
	v_pk_mul_f32 v[180:181], v[34:35], v[36:37] op_sel_hi:[1,0]
	v_pk_mul_f32 v[34:35], v[28:29], v[36:37] op_sel_hi:[1,0]
	v_cndmask_b32_e32 v24, v24, v25, vcc
	v_rsq_f32_e32 v24, v24
	s_setprio 0
	v_pk_mul_f32 v[28:29], v[12:13], v[36:37] op_sel_hi:[1,0]
	v_lshlrev_b32_e32 v54, 16, v88
	v_and_b32_e32 v55, 0xffff0000, v88
	v_mul_f32_e32 v12, 0x45800000, v24
	v_cndmask_b32_e32 v12, v24, v12, vcc
	v_pk_mul_f32 v[146:147], v[22:23], v[12:13] op_sel_hi:[1,0]
	v_pk_mul_f32 v[22:23], v[6:7], v[12:13] op_sel_hi:[1,0]
	v_mov_b32_e32 v6, v2
	v_mov_b32_e32 v7, v2
	v_pk_mul_f32 v[148:149], v[20:21], v[12:13] op_sel_hi:[1,0]
	v_pk_mul_f32 v[20:21], v[4:5], v[12:13] op_sel_hi:[1,0]
	v_mov_b32_e32 v4, v2
	v_mov_b32_dpp v6, v192 row_shr:2 row_mask:0xf bank_mask:0xf
	v_mov_b32_e32 v5, v2
	v_mov_b32_dpp v7, v193 row_shr:2 row_mask:0xf bank_mask:0xf
	v_lshlrev_b32_e32 v48, 16, v89
	v_and_b32_e32 v49, 0xffff0000, v89
	v_mov_b32_dpp v4, v192 row_shr:1 row_mask:0xf bank_mask:0xf
	v_mov_b32_dpp v5, v193 row_shr:1 row_mask:0xf bank_mask:0xf
	v_mov_b32_e32 v88, v2
	v_mov_b32_e32 v89, v2
	v_pk_fma_f32 v[6:7], v[50:51], v[6:7], v[62:63]
	v_pk_mul_f32 v[228:229], v[58:59], v[144:145] op_sel_hi:[1,0]
	v_pk_mul_f32 v[224:225], v[52:53], v[44:45] op_sel_hi:[1,0]
	v_pk_mul_f32 v[220:221], v[42:43], v[44:45] op_sel_hi:[1,0]
	v_pk_mul_f32 v[218:219], v[40:41], v[44:45] op_sel_hi:[1,0]
	v_pk_mul_f32 v[204:205], v[38:39], v[44:45] op_sel_hi:[1,0]
	v_lshlrev_b32_e32 v58, 16, v85
	v_and_b32_e32 v59, 0xffff0000, v85
	v_lshlrev_b32_e32 v44, 16, v92
	v_and_b32_e32 v45, 0xffff0000, v92
	v_lshlrev_b32_e32 v66, 16, v97
	v_and_b32_e32 v67, 0xffff0000, v97
	v_mov_b32_e32 v84, v2
	v_mov_b32_dpp v88, v194 row_shr:2 row_mask:0xf bank_mask:0xf
	v_mov_b32_e32 v85, v2
	v_mov_b32_dpp v89, v195 row_shr:2 row_mask:0xf bank_mask:0xf
	v_pk_fma_f32 v[4:5], v[54:55], v[4:5], v[6:7]
	v_mov_b32_dpp v84, v194 row_shr:1 row_mask:0xf bank_mask:0xf
	v_mov_b32_dpp v85, v195 row_shr:1 row_mask:0xf bank_mask:0xf
	v_pk_fma_f32 v[88:89], v[58:59], v[88:89], v[66:67]
	v_pk_fma_f32 v[4:5], v[192:193], v[44:45], v[4:5]
	s_setprio 1
	v_pk_fma_f32 v[6:7], v[48:49], v[84:85], v[88:89]
	v_mul_f32_e32 v88, 0xbfb8aa3b, v4
	v_exp_f32_e32 v88, v88
	v_pk_mul_f32 v[232:233], v[64:65], v[144:145] op_sel_hi:[1,0]
	v_pk_mul_f32 v[216:217], v[60:61], v[144:145] op_sel_hi:[1,0]
	v_pk_mul_f32 v[212:213], v[46:47], v[144:145] op_sel_hi:[1,0]
	v_pk_mul_f32 v[144:145], v[10:11], v[12:13] op_sel_hi:[1,0]
	v_mov_b32_e32 v10, v2
	v_mov_b32_e32 v11, v2
	v_mov_b32_e32 v96, v2
	v_mov_b32_e32 v97, v2
	v_pk_mul_f32 v[122:123], v[8:9], v[12:13] op_sel_hi:[1,0]
	v_lshlrev_b32_e32 v52, 16, v93
	v_and_b32_e32 v53, 0xffff0000, v93
	v_lshlrev_b32_e32 v46, 16, v100
	v_and_b32_e32 v47, 0xffff0000, v100
	v_lshlrev_b32_e32 v56, 16, v101
	v_and_b32_e32 v57, 0xffff0000, v101
	v_lshlrev_b32_e32 v60, 16, v112
	v_and_b32_e32 v61, 0xffff0000, v112
	v_lshlrev_b32_e32 v64, 16, v113
	v_and_b32_e32 v65, 0xffff0000, v113
	v_mov_b32_e32 v8, v2
	v_mov_b32_dpp v10, v188 row_shr:2 row_mask:0xf bank_mask:0xf
	v_mov_b32_e32 v9, v2
	v_mov_b32_dpp v11, v189 row_shr:2 row_mask:0xf bank_mask:0xf
	v_mov_b32_e32 v92, v2
	v_mov_b32_dpp v96, v190 row_shr:2 row_mask:0xf bank_mask:0xf
	v_mov_b32_e32 v93, v2
	v_mov_b32_dpp v97, v191 row_shr:2 row_mask:0xf bank_mask:0xf
	v_lshlrev_b32_e32 v38, 16, v104
	v_and_b32_e32 v39, 0xffff0000, v104
	v_lshlrev_b32_e32 v40, 16, v105
	v_and_b32_e32 v41, 0xffff0000, v105
	v_mov_b32_dpp v8, v188 row_shr:1 row_mask:0xf bank_mask:0xf
	v_mov_b32_dpp v9, v189 row_shr:1 row_mask:0xf bank_mask:0xf
	v_mov_b32_dpp v92, v190 row_shr:1 row_mask:0xf bank_mask:0xf
	v_mov_b32_dpp v93, v191 row_shr:1 row_mask:0xf bank_mask:0xf
	v_pk_fma_f32 v[84:85], v[56:57], v[96:97], v[64:65]
	v_pk_fma_f32 v[10:11], v[46:47], v[10:11], v[60:61]
	v_pk_mul_f32 v[182:183], v[32:33], v[36:37] op_sel_hi:[1,0]
	v_pk_fma_f32 v[8:9], v[38:39], v[8:9], v[10:11]
; __device__ __forceinline__ unsigned cvt_pk_bf16(float lo, float hi) { unsigned r; asm volatile("v_cvt_pk_bf16_f32 %0, %1, %2" : "=v"(r) : "v"(lo), "v"(hi)); return r; }
; __device__ __forceinline__ float fexp2(float x) { return __builtin_amdgcn_exp2f(x); }
; __device__ __forceinline__ float frcp(float x) { return __builtin_amdgcn_rcpf(x); }
; __device__ __forceinline__ float dpp_shr1(float old, float src) { return __int_as_float(__builtin_amdgcn_update_dpp(__float_as_int(old), __float_as_int(src), 0x111, 0xf, 0xf, false)); }
; __device__ __forceinline__ float dpp_shr2(float old, float src) { return __int_as_float(__builtin_amdgcn_update_dpp(__float_as_int(old), __float_as_int(src), 0x112, 0xf, 0xf, false)); }
; __device__ __forceinline__ float dpp_ror1(float src) { return __int_as_float(__builtin_amdgcn_mov_dpp(__float_as_int(src), 0x121, 0xf, 0xf, true)); }
; __device__ __forceinline__ float dpp_ror2(float src) { return __int_as_float(__builtin_amdgcn_mov_dpp(__float_as_int(src), 0x122, 0xf, 0xf, true)); }
;     __device__ __forceinline__ void operator()(f32x4 (&acc)[2][2][4][2], const Unit& u, int wr, int wc, int fr, int fq) const {
;     ...
;                 for (int m = 0; m < 4; ++m) {
;                     const f32x4 zg = acc[ai][0][m][n], zv = acc[ai][1][m][n];
;                     f32x4 g1, g2, v1, v2;
; #pragma unroll
;                     for (int j = 0; j < 4; ++j) { g1[j] = dpp_shr1(pg1[j], zg[j]); g2[j] = dpp_shr2(pg2[j], zg[j]); v1[j] = dpp_shr1(pv1[j], zv[j]); v2[j] = dpp_shr2(pv2[j], zv[j]);
;                         pg1[j] = dpp_ror1(zg[j]); pg2[j] = dpp_ror2(zg[j]); pv1[j] = dpp_ror1(zv[j]); pv2[j] = dpp_ror2(zv[j]); }
;                     const f32x4 cg_ = bg + wg0 * g2 + wg1 * g1 + wg2 * zg, cv_ = bv + wv0 * v2 + wv1 * v1 + wv2 * zv;
;                     float o[4];
; #pragma unroll
;                     for (int j = 0; j < 4; ++j) o[j] = cg_[j] * frcp(1.0f + fexp2(-1.4426950409f * cg_[j])) * cv_[j];
;                     pk[m][n][0] = cvt_pk_bf16(o[0], o[1]); pk[m][n][1] = cvt_pk_bf16(o[2], o[3]);
	s_setprio 0
	v_pk_fma_f32 v[10:11], v[40:41], v[92:93], v[84:85]
	v_add_f32_e32 v84, 1.0, v88
	v_rcp_f32_e32 v84, v84
	v_mul_f32_e32 v85, 0xbfb8aa3b, v5
	v_exp_f32_e32 v85, v85
	v_pk_mul_f32 v[32:33], v[30:31], v[36:37] op_sel_hi:[1,0]
	v_pk_mul_f32 v[178:179], v[26:27], v[36:37] op_sel_hi:[1,0]
	v_pk_mul_f32 v[30:31], v[14:15], v[36:37] op_sel_hi:[1,0]
	v_lshlrev_b32_e32 v36, 16, v108
	v_and_b32_e32 v37, 0xffff0000, v108
	v_pk_fma_f32 v[6:7], v[194:195], v[52:53], v[6:7]
	v_pk_fma_f32 v[8:9], v[188:189], v[36:37], v[8:9]
	v_mul_f32_e32 v4, v4, v84
	v_mul_f32_e32 v4, v8, v4
	v_add_f32_e32 v8, 1.0, v85
	v_mul_f32_e32 v84, 0xbfb8aa3b, v6
	v_rcp_f32_e32 v8, v8
	v_exp_f32_e32 v84, v84
	v_mov_b32_dpp v14, v192 row_ror:2 row_mask:0xf bank_mask:0xf bound_ctrl:1
	v_mov_b32_dpp v15, v193 row_ror:2 row_mask:0xf bank_mask:0xf bound_ctrl:1
	v_mul_f32_e32 v5, v5, v8
	v_add_f32_e32 v8, 1.0, v84
	v_rcp_f32_e32 v8, v8
	v_pk_mul_f32 v[24:25], v[18:19], v[12:13] op_sel_hi:[1,0]
	v_pk_mul_f32 v[26:27], v[16:17], v[12:13] op_sel_hi:[1,0]
	v_mov_b32_dpp v12, v192 row_ror:1 row_mask:0xf bank_mask:0xf bound_ctrl:1
	v_mov_b32_dpp v13, v193 row_ror:1 row_mask:0xf bank_mask:0xf bound_ctrl:1
	v_mov_b32_dpp v14, v232 row_shr:2 row_mask:0xf bank_mask:0xf
	v_mov_b32_dpp v15, v233 row_shr:2 row_mask:0xf bank_mask:0xf
	v_mov_b32_dpp v104, v194 row_ror:2 row_mask:0xf bank_mask:0xf bound_ctrl:1
	v_mov_b32_dpp v105, v195 row_ror:2 row_mask:0xf bank_mask:0xf bound_ctrl:1
	v_mov_b32_dpp v12, v232 row_shr:1 row_mask:0xf bank_mask:0xf
	v_mov_b32_dpp v13, v233 row_shr:1 row_mask:0xf bank_mask:0xf
	v_pk_fma_f32 v[14:15], v[50:51], v[14:15], v[62:63]
	v_mov_b32_dpp v100, v194 row_ror:1 row_mask:0xf bank_mask:0xf bound_ctrl:1
	v_mov_b32_dpp v101, v195 row_ror:1 row_mask:0xf bank_mask:0xf bound_ctrl:1
	v_mov_b32_dpp v104, v230 row_shr:2 row_mask:0xf bank_mask:0xf
	v_mov_b32_dpp v105, v231 row_shr:2 row_mask:0xf bank_mask:0xf
	v_pk_fma_f32 v[12:13], v[54:55], v[12:13], v[14:15]
	v_mul_f32_e32 v5, v9, v5
	v_mul_f32_e32 v6, v6, v8
	v_mov_b32_dpp v100, v230 row_shr:1 row_mask:0xf bank_mask:0xf
	s_setprio 1
	v_mov_b32_dpp v101, v231 row_shr:1 row_mask:0xf bank_mask:0xf
	v_pk_fma_f32 v[8:9], v[58:59], v[104:105], v[66:67]
	v_pk_fma_f32 v[12:13], v[232:233], v[44:45], v[12:13]
	v_pk_fma_f32 v[8:9], v[48:49], v[100:101], v[8:9]
	v_mul_f32_e32 v100, 0xbfb8aa3b, v12
	v_exp_f32_e32 v100, v100
	v_mov_b32_dpp v18, v188 row_ror:2 row_mask:0xf bank_mask:0xf bound_ctrl:1
	v_mov_b32_dpp v19, v189 row_ror:2 row_mask:0xf bank_mask:0xf bound_ctrl:1
	v_mov_b32_dpp v16, v188 row_ror:1 row_mask:0xf bank_mask:0xf bound_ctrl:1
	v_mov_b32_dpp v17, v189 row_ror:1 row_mask:0xf bank_mask:0xf bound_ctrl:1
	v_mov_b32_dpp v18, v226 row_shr:2 row_mask:0xf bank_mask:0xf
	v_mov_b32_dpp v19, v227 row_shr:2 row_mask:0xf bank_mask:0xf
	v_mov_b32_dpp v16, v226 row_shr:1 row_mask:0xf bank_mask:0xf
	v_mov_b32_dpp v17, v227 row_shr:1 row_mask:0xf bank_mask:0xf
	v_pk_fma_f32 v[18:19], v[46:47], v[18:19], v[60:61]
	v_mul_f32_e32 v85, 0xbfb8aa3b, v7
	v_pk_fma_f32 v[16:17], v[38:39], v[16:17], v[18:19]
	v_add_f32_e32 v18, 1.0, v100
	v_rcp_f32_e32 v18, v18
	v_mul_f32_e32 v19, 0xbfb8aa3b, v13
	v_exp_f32_e32 v19, v19
	v_exp_f32_e32 v85, v85
	v_pk_fma_f32 v[8:9], v[230:231], v[52:53], v[8:9]
	v_pk_fma_f32 v[16:17], v[226:227], v[36:37], v[16:17]
	v_mul_f32_e32 v12, v12, v18
	v_mul_f32_e32 v12, v16, v12
	v_add_f32_e32 v16, 1.0, v19
	v_mul_f32_e32 v18, 0xbfb8aa3b, v8
	v_rcp_f32_e32 v16, v16
	v_exp_f32_e32 v18, v18
	v_mul_f32_e32 v19, 0xbfb8aa3b, v9
	v_add_f32_e32 v84, 1.0, v85
	v_exp_f32_e32 v19, v19
	v_rcp_f32_e32 v84, v84
	v_mul_f32_e32 v13, v13, v16
	v_add_f32_e32 v16, 1.0, v18
	v_lshlrev_b32_e32 v42, 16, v109
	v_and_b32_e32 v43, 0xffff0000, v109
	v_mov_b32_dpp v112, v190 row_ror:2 row_mask:0xf bank_mask:0xf bound_ctrl:1
	v_mov_b32_dpp v113, v191 row_ror:2 row_mask:0xf bank_mask:0xf bound_ctrl:1
	v_rcp_f32_e32 v16, v16
	v_add_f32_e32 v18, 1.0, v19
	s_setprio 0
	v_mov_b32_dpp v108, v190 row_ror:1 row_mask:0xf bank_mask:0xf bound_ctrl:1
	v_mov_b32_dpp v109, v191 row_ror:1 row_mask:0xf bank_mask:0xf bound_ctrl:1
	v_pk_fma_f32 v[10:11], v[190:191], v[42:43], v[10:11]
	v_mul_f32_e32 v7, v7, v84
	v_mov_b32_dpp v112, v228 row_shr:2 row_mask:0xf bank_mask:0xf
	v_mov_b32_dpp v113, v229 row_shr:2 row_mask:0xf bank_mask:0xf
	v_rcp_f32_e32 v18, v18
	v_mul_f32_e32 v6, v10, v6
	v_mul_f32_e32 v7, v11, v7
	v_mov_b32_dpp v10, v232 row_ror:2 row_mask:0xf bank_mask:0xf bound_ctrl:1
	v_mov_b32_dpp v11, v233 row_ror:2 row_mask:0xf bank_mask:0xf bound_ctrl:1
	v_mov_b32_dpp v108, v228 row_shr:1 row_mask:0xf bank_mask:0xf
	v_mov_b32_dpp v109, v229 row_shr:1 row_mask:0xf bank_mask:0xf
	v_pk_fma_f32 v[14:15], v[56:57], v[112:113], v[64:65]
	v_cvt_pk_bf16_f32 v4, v4, v5
	v_cvt_pk_bf16_f32 v5, v6, v7
	v_mov_b32_dpp v6, v232 row_ror:1 row_mask:0xf bank_mask:0xf bound_ctrl:1
	v_mov_b32_dpp v7, v233 row_ror:1 row_mask:0xf bank_mask:0xf bound_ctrl:1
	v_pk_fma_f32 v[14:15], v[40:41], v[108:109], v[14:15]
	v_mov_b32_dpp v10, v224 row_shr:2 row_mask:0xf bank_mask:0xf
	v_mov_b32_dpp v11, v225 row_shr:2 row_mask:0xf bank_mask:0xf
	v_mov_b32_dpp v96, v230 row_ror:2 row_mask:0xf bank_mask:0xf bound_ctrl:1
	v_mov_b32_dpp v97, v231 row_ror:2 row_mask:0xf bank_mask:0xf bound_ctrl:1
	v_pk_fma_f32 v[14:15], v[228:229], v[42:43], v[14:15]
	v_mul_f32_e32 v8, v8, v16
	v_mov_b32_dpp v6, v224 row_shr:1 row_mask:0xf bank_mask:0xf
	v_mov_b32_dpp v7, v225 row_shr:1 row_mask:0xf bank_mask:0xf
	v_pk_fma_f32 v[10:11], v[50:51], v[10:11], v[62:63]
	v_mov_b32_dpp v92, v230 row_ror:1 row_mask:0xf bank_mask:0xf bound_ctrl:1
	v_mov_b32_dpp v93, v231 row_ror:1 row_mask:0xf bank_mask:0xf bound_ctrl:1
; __device__ __forceinline__ unsigned cvt_pk_bf16(float lo, float hi) { unsigned r; asm volatile("v_cvt_pk_bf16_f32 %0, %1, %2" : "=v"(r) : "v"(lo), "v"(hi)); return r; }
; __device__ __forceinline__ float fexp2(float x) { return __builtin_amdgcn_exp2f(x); }
; __device__ __forceinline__ float frcp(float x) { return __builtin_amdgcn_rcpf(x); }
; __device__ __forceinline__ float dpp_shr1(float old, float src) { return __int_as_float(__builtin_amdgcn_update_dpp(__float_as_int(old), __float_as_int(src), 0x111, 0xf, 0xf, false)); }
; __device__ __forceinline__ float dpp_shr2(float old, float src) { return __int_as_float(__builtin_amdgcn_update_dpp(__float_as_int(old), __float_as_int(src), 0x112, 0xf, 0xf, false)); }
; __device__ __forceinline__ float dpp_ror1(float src) { return __int_as_float(__builtin_amdgcn_mov_dpp(__float_as_int(src), 0x121, 0xf, 0xf, true)); }
; __device__ __forceinline__ float dpp_ror2(float src) { return __int_as_float(__builtin_amdgcn_mov_dpp(__float_as_int(src), 0x122, 0xf, 0xf, true)); }
;     __device__ __forceinline__ void operator()(f32x4 (&acc)[2][2][4][2], const Unit& u, int wr, int wc, int fr, int fq) const {
;     ...
;                 for (int m = 0; m < 4; ++m) {
;                     const f32x4 zg = acc[ai][0][m][n], zv = acc[ai][1][m][n];
;                     f32x4 g1, g2, v1, v2;
; #pragma unroll
;                     for (int j = 0; j < 4; ++j) { g1[j] = dpp_shr1(pg1[j], zg[j]); g2[j] = dpp_shr2(pg2[j], zg[j]); v1[j] = dpp_shr1(pv1[j], zv[j]); v2[j] = dpp_shr2(pv2[j], zv[j]);
;                         pg1[j] = dpp_ror1(zg[j]); pg2[j] = dpp_ror2(zg[j]); pv1[j] = dpp_ror1(zv[j]); pv2[j] = dpp_ror2(zv[j]); }
;                     const f32x4 cg_ = bg + wg0 * g2 + wg1 * g1 + wg2 * zg, cv_ = bv + wv0 * v2 + wv1 * v1 + wv2 * zv;
;                     float o[4];
; #pragma unroll
;                     for (int j = 0; j < 4; ++j) o[j] = cg_[j] * frcp(1.0f + fexp2(-1.4426950409f * cg_[j])) * cv_[j];
;                     pk[m][n][0] = cvt_pk_bf16(o[0], o[1]); pk[m][n][1] = cvt_pk_bf16(o[2], o[3]);
	v_mul_f32_e32 v13, v17, v13
	v_mul_f32_e32 v14, v14, v8
	v_mul_f32_e32 v8, v9, v18
	v_mov_b32_dpp v96, v222 row_shr:2 row_mask:0xf bank_mask:0xf
	v_mov_b32_dpp v97, v223 row_shr:2 row_mask:0xf bank_mask:0xf
	v_pk_fma_f32 v[6:7], v[54:55], v[6:7], v[10:11]
	v_mul_f32_e32 v9, v15, v8
	s_setprio 1
	v_cvt_pk_bf16_f32 v8, v12, v13
	v_mov_b32_dpp v92, v222 row_shr:1 row_mask:0xf bank_mask:0xf
	v_mov_b32_dpp v93, v223 row_shr:1 row_mask:0xf bank_mask:0xf
	v_pk_fma_f32 v[12:13], v[58:59], v[96:97], v[66:67]
	v_pk_fma_f32 v[6:7], v[224:225], v[44:45], v[6:7]
	v_pk_fma_f32 v[10:11], v[48:49], v[92:93], v[12:13]
	v_mul_f32_e32 v92, 0xbfb8aa3b, v6
	v_exp_f32_e32 v92, v92
	v_mov_b32_dpp v88, v226 row_ror:2 row_mask:0xf bank_mask:0xf bound_ctrl:1
	v_mov_b32_dpp v89, v227 row_ror:2 row_mask:0xf bank_mask:0xf bound_ctrl:1
	v_mov_b32_dpp v84, v226 row_ror:1 row_mask:0xf bank_mask:0xf bound_ctrl:1
	v_mov_b32_dpp v85, v227 row_ror:1 row_mask:0xf bank_mask:0xf bound_ctrl:1
	v_mov_b32_dpp v88, v218 row_shr:2 row_mask:0xf bank_mask:0xf
	v_mov_b32_dpp v89, v219 row_shr:2 row_mask:0xf bank_mask:0xf
	v_mov_b32_dpp v84, v218 row_shr:1 row_mask:0xf bank_mask:0xf
	v_mov_b32_dpp v85, v219 row_shr:1 row_mask:0xf bank_mask:0xf
	v_pk_fma_f32 v[88:89], v[46:47], v[88:89], v[60:61]
	v_pk_fma_f32 v[10:11], v[222:223], v[52:53], v[10:11]
	v_pk_fma_f32 v[84:85], v[38:39], v[84:85], v[88:89]
	v_add_f32_e32 v88, 1.0, v92
	v_rcp_f32_e32 v88, v88
	v_mul_f32_e32 v89, 0xbfb8aa3b, v7
	v_exp_f32_e32 v89, v89
	v_pk_fma_f32 v[84:85], v[218:219], v[36:37], v[84:85]
	v_mul_f32_e32 v6, v6, v88
	v_mul_f32_e32 v6, v84, v6
	v_add_f32_e32 v84, 1.0, v89
	v_mul_f32_e32 v88, 0xbfb8aa3b, v10
	v_mul_f32_e32 v89, 0xbfb8aa3b, v11
	v_rcp_f32_e32 v84, v84
	v_exp_f32_e32 v88, v88
	v_exp_f32_e32 v89, v89
	v_mov_b32_dpp v190, v228 row_ror:2 row_mask:0xf bank_mask:0xf bound_ctrl:1
	v_mul_f32_e32 v7, v7, v84
	v_add_f32_e32 v84, 1.0, v88
	v_add_f32_e32 v88, 1.0, v89
	v_mov_b32_dpp v191, v229 row_ror:2 row_mask:0xf bank_mask:0xf bound_ctrl:1
	v_rcp_f32_e32 v84, v84
	v_rcp_f32_e32 v88, v88
	v_mov_b32_dpp v188, v228 row_ror:1 row_mask:0xf bank_mask:0xf bound_ctrl:1
	v_mov_b32_dpp v189, v229 row_ror:1 row_mask:0xf bank_mask:0xf bound_ctrl:1
	s_setprio 0
	v_mov_b32_dpp v190, v220 row_shr:2 row_mask:0xf bank_mask:0xf
	v_mov_b32_dpp v191, v221 row_shr:2 row_mask:0xf bank_mask:0xf
	v_mov_b32_dpp v188, v220 row_shr:1 row_mask:0xf bank_mask:0xf
	v_mov_b32_dpp v189, v221 row_shr:1 row_mask:0xf bank_mask:0xf
	v_pk_fma_f32 v[12:13], v[56:57], v[190:191], v[64:65]
	v_mov_b32_dpp v16, v224 row_ror:2 row_mask:0xf bank_mask:0xf bound_ctrl:1
	v_pk_fma_f32 v[12:13], v[40:41], v[188:189], v[12:13]
	v_mov_b32_dpp v17, v225 row_ror:2 row_mask:0xf bank_mask:0xf bound_ctrl:1
	v_pk_fma_f32 v[12:13], v[220:221], v[42:43], v[12:13]
	v_mul_f32_e32 v10, v10, v84
	v_mul_f32_e32 v11, v11, v88
	v_cvt_pk_bf16_f32 v9, v14, v9
	v_mov_b32_dpp v14, v224 row_ror:1 row_mask:0xf bank_mask:0xf bound_ctrl:1
	v_mov_b32_dpp v15, v225 row_ror:1 row_mask:0xf bank_mask:0xf bound_ctrl:1
	v_mul_f32_e32 v10, v12, v10
	v_mul_f32_e32 v11, v13, v11
	v_mov_b32_dpp v16, v186 row_shr:2 row_mask:0xf bank_mask:0xf
	v_mov_b32_dpp v17, v187 row_shr:2 row_mask:0xf bank_mask:0xf
	v_mul_f32_e32 v7, v85, v7
	v_cvt_pk_bf16_f32 v12, v6, v7
	v_cvt_pk_bf16_f32 v13, v10, v11
	v_mov_b32_dpp v14, v186 row_shr:1 row_mask:0xf bank_mask:0xf
	v_mov_b32_dpp v15, v187 row_shr:1 row_mask:0xf bank_mask:0xf
	v_pk_fma_f32 v[10:11], v[50:51], v[16:17], v[62:63]
	v_mov_b32_dpp v100, v218 row_ror:2 row_mask:0xf bank_mask:0xf bound_ctrl:1
	v_pk_fma_f32 v[10:11], v[54:55], v[14:15], v[10:11]
	v_mov_b32_dpp v101, v219 row_ror:2 row_mask:0xf bank_mask:0xf bound_ctrl:1
	v_pk_fma_f32 v[10:11], v[186:187], v[44:45], v[10:11]
	v_mov_b32_dpp v18, v218 row_ror:1 row_mask:0xf bank_mask:0xf bound_ctrl:1
	v_mul_f32_e32 v84, 0xbfb8aa3b, v10
	v_exp_f32_e32 v84, v84
	v_mov_b32_dpp v19, v219 row_ror:1 row_mask:0xf bank_mask:0xf bound_ctrl:1
	v_mov_b32_dpp v100, v150 row_shr:2 row_mask:0xf bank_mask:0xf
	v_mov_b32_dpp v101, v151 row_shr:2 row_mask:0xf bank_mask:0xf
	v_mov_b32_dpp v18, v150 row_shr:1 row_mask:0xf bank_mask:0xf
	v_mov_b32_dpp v19, v151 row_shr:1 row_mask:0xf bank_mask:0xf
	s_setprio 1
	v_pk_fma_f32 v[16:17], v[46:47], v[100:101], v[60:61]
	v_mov_b32_dpp v108, v222 row_ror:2 row_mask:0xf bank_mask:0xf bound_ctrl:1
	v_pk_fma_f32 v[16:17], v[38:39], v[18:19], v[16:17]
	v_add_f32_e32 v18, 1.0, v84
	v_mov_b32_dpp v109, v223 row_ror:2 row_mask:0xf bank_mask:0xf bound_ctrl:1
	v_rcp_f32_e32 v18, v18
	v_mul_f32_e32 v19, 0xbfb8aa3b, v11
	v_mov_b32_dpp v104, v222 row_ror:1 row_mask:0xf bank_mask:0xf bound_ctrl:1
	v_mov_b32_dpp v105, v223 row_ror:1 row_mask:0xf bank_mask:0xf bound_ctrl:1
	v_mov_b32_dpp v108, v184 row_shr:2 row_mask:0xf bank_mask:0xf
	v_mov_b32_dpp v109, v185 row_shr:2 row_mask:0xf bank_mask:0xf
	v_exp_f32_e32 v19, v19
	v_mov_b32_dpp v104, v184 row_shr:1 row_mask:0xf bank_mask:0xf
	v_mov_b32_dpp v105, v185 row_shr:1 row_mask:0xf bank_mask:0xf
	v_pk_fma_f32 v[6:7], v[58:59], v[108:109], v[66:67]
	v_pk_fma_f32 v[16:17], v[150:151], v[36:37], v[16:17]
	v_pk_fma_f32 v[6:7], v[48:49], v[104:105], v[6:7]
	v_mul_f32_e32 v10, v10, v18
	v_pk_fma_f32 v[6:7], v[184:185], v[52:53], v[6:7]
	v_mul_f32_e32 v10, v16, v10
	v_add_f32_e32 v16, 1.0, v19
	v_mul_f32_e32 v18, 0xbfb8aa3b, v6
	v_mul_f32_e32 v19, 0xbfb8aa3b, v7
	v_rcp_f32_e32 v16, v16
	v_exp_f32_e32 v18, v18
	v_exp_f32_e32 v19, v19
	v_mov_b32_dpp v192, v220 row_ror:2 row_mask:0xf bank_mask:0xf bound_ctrl:1
	v_mul_f32_e32 v11, v11, v16
	v_add_f32_e32 v16, 1.0, v18
	v_add_f32_e32 v18, 1.0, v19
	v_mov_b32_dpp v193, v221 row_ror:2 row_mask:0xf bank_mask:0xf bound_ctrl:1
; __device__ __forceinline__ unsigned cvt_pk_bf16(float lo, float hi) { unsigned r; asm volatile("v_cvt_pk_bf16_f32 %0, %1, %2" : "=v"(r) : "v"(lo), "v"(hi)); return r; }
; __device__ __forceinline__ float fexp2(float x) { return __builtin_amdgcn_exp2f(x); }
; __device__ __forceinline__ float frcp(float x) { return __builtin_amdgcn_rcpf(x); }
; __device__ __forceinline__ float dpp_shr1(float old, float src) { return __int_as_float(__builtin_amdgcn_update_dpp(__float_as_int(old), __float_as_int(src), 0x111, 0xf, 0xf, false)); }
; __device__ __forceinline__ float dpp_shr2(float old, float src) { return __int_as_float(__builtin_amdgcn_update_dpp(__float_as_int(old), __float_as_int(src), 0x112, 0xf, 0xf, false)); }
; __device__ __forceinline__ float dpp_ror1(float src) { return __int_as_float(__builtin_amdgcn_mov_dpp(__float_as_int(src), 0x121, 0xf, 0xf, true)); }
; __device__ __forceinline__ float dpp_ror2(float src) { return __int_as_float(__builtin_amdgcn_mov_dpp(__float_as_int(src), 0x122, 0xf, 0xf, true)); }
;     __device__ __forceinline__ void operator()(f32x4 (&acc)[2][2][4][2], const Unit& u, int wr, int wc, int fr, int fq) const {
;     ...
;                 const f32x4 wg0 = CQ4(0, 0), wg1 = CQ4(0, 1), wg2 = CQ4(0, 2), bg = CQ4(0, 3);
;                 const f32x4 wv0 = CQ4(1, 0), wv1 = CQ4(1, 1), wv2 = CQ4(1, 2), bv = CQ4(1, 3);
;     ...
;                 for (int m = 0; m < 4; ++m) {
;                     const f32x4 zg = acc[ai][0][m][n], zv = acc[ai][1][m][n];
;                     f32x4 g1, g2, v1, v2;
; #pragma unroll
;                     for (int j = 0; j < 4; ++j) { g1[j] = dpp_shr1(pg1[j], zg[j]); g2[j] = dpp_shr2(pg2[j], zg[j]); v1[j] = dpp_shr1(pv1[j], zv[j]); v2[j] = dpp_shr2(pv2[j], zv[j]);
;                         pg1[j] = dpp_ror1(zg[j]); pg2[j] = dpp_ror2(zg[j]); pv1[j] = dpp_ror1(zv[j]); pv2[j] = dpp_ror2(zv[j]); }
;                     const f32x4 cg_ = bg + wg0 * g2 + wg1 * g1 + wg2 * zg, cv_ = bv + wv0 * v2 + wv1 * v1 + wv2 * zv;
;                     float o[4];
; #pragma unroll
;                     for (int j = 0; j < 4; ++j) o[j] = cg_[j] * frcp(1.0f + fexp2(-1.4426950409f * cg_[j])) * cv_[j];
;                     pk[m][n][0] = cvt_pk_bf16(o[0], o[1]); pk[m][n][1] = cvt_pk_bf16(o[2], o[3]);
	v_rcp_f32_e32 v16, v16
	v_rcp_f32_e32 v18, v18
	v_mov_b32_dpp v112, v220 row_ror:1 row_mask:0xf bank_mask:0xf bound_ctrl:1
	v_mov_b32_dpp v113, v221 row_ror:1 row_mask:0xf bank_mask:0xf bound_ctrl:1
	v_mov_b32_dpp v192, v160 row_shr:2 row_mask:0xf bank_mask:0xf
	v_mov_b32_dpp v193, v161 row_shr:2 row_mask:0xf bank_mask:0xf
	v_mov_b32_dpp v112, v160 row_shr:1 row_mask:0xf bank_mask:0xf
	v_mov_b32_dpp v113, v161 row_shr:1 row_mask:0xf bank_mask:0xf
	v_pk_fma_f32 v[14:15], v[56:57], v[192:193], v[64:65]
	v_mul_f32_e32 v11, v17, v11
	v_pk_fma_f32 v[14:15], v[40:41], v[112:113], v[14:15]
	s_setprio 0
	v_mul_f32_e32 v6, v6, v16
	v_pk_fma_f32 v[14:15], v[160:161], v[42:43], v[14:15]
	v_mul_f32_e32 v7, v7, v18
	v_mul_f32_e32 v6, v14, v6
	v_mul_f32_e32 v7, v15, v7
	v_cvt_pk_bf16_f32 v16, v10, v11
	v_mov_b32_e32 v10, v2
	v_mov_b32_e32 v11, v2
	v_cvt_pk_bf16_f32 v17, v6, v7
	v_lshlrev_b32_e32 v100, 16, v86
	v_and_b32_e32 v101, 0xffff0000, v86
	v_lshlrev_b32_e32 v150, 16, v98
	v_and_b32_e32 v151, 0xffff0000, v98
	v_mov_b32_e32 v6, v2
	v_mov_b32_dpp v10, v156 row_shr:2 row_mask:0xf bank_mask:0xf
	v_mov_b32_e32 v7, v2
	v_mov_b32_dpp v11, v157 row_shr:2 row_mask:0xf bank_mask:0xf
	v_mov_b32_e32 v190, v2
	v_mov_b32_e32 v191, v2
	v_lshlrev_b32_e32 v112, 16, v87
	v_and_b32_e32 v113, 0xffff0000, v87
	v_lshlrev_b32_e32 v108, 16, v90
	v_and_b32_e32 v109, 0xffff0000, v90
	v_lshlrev_b32_e32 v160, 16, v99
	v_and_b32_e32 v161, 0xffff0000, v99
	v_mov_b32_dpp v6, v156 row_shr:1 row_mask:0xf bank_mask:0xf
	v_mov_b32_dpp v7, v157 row_shr:1 row_mask:0xf bank_mask:0xf
	v_mov_b32_e32 v188, v2
	v_mov_b32_dpp v190, v158 row_shr:2 row_mask:0xf bank_mask:0xf
	v_mov_b32_e32 v189, v2
	v_mov_b32_dpp v191, v159 row_shr:2 row_mask:0xf bank_mask:0xf
	v_pk_fma_f32 v[10:11], v[100:101], v[10:11], v[150:151]
	v_lshlrev_b32_e32 v96, 16, v91
	v_and_b32_e32 v97, 0xffff0000, v91
	v_lshlrev_b32_e32 v92, 16, v94
	v_and_b32_e32 v93, 0xffff0000, v94
	v_mov_b32_dpp v188, v158 row_shr:1 row_mask:0xf bank_mask:0xf
	v_mov_b32_dpp v189, v159 row_shr:1 row_mask:0xf bank_mask:0xf
	s_setprio 1
	v_pk_fma_f32 v[190:191], v[112:113], v[190:191], v[160:161]
	v_pk_fma_f32 v[6:7], v[108:109], v[6:7], v[10:11]
	v_lshlrev_b32_e32 v104, 16, v95
	v_and_b32_e32 v105, 0xffff0000, v95
	v_pk_fma_f32 v[10:11], v[96:97], v[188:189], v[190:191]
	v_pk_fma_f32 v[6:7], v[156:157], v[92:93], v[6:7]
	v_mov_b32_dpp v218, v158 row_ror:1 row_mask:0xf bank_mask:0xf bound_ctrl:1
	v_mov_b32_dpp v220, v158 row_ror:2 row_mask:0xf bank_mask:0xf bound_ctrl:1
	v_pk_fma_f32 v[10:11], v[158:159], v[104:105], v[10:11]
	v_mul_f32_e32 v158, 0xbfb8aa3b, v6
	v_mov_b32_e32 v18, v2
	v_mov_b32_e32 v19, v2
	v_mov_b32_e32 v194, v2
	v_mov_b32_e32 v195, v2
	v_exp_f32_e32 v158, v158
	v_lshlrev_b32_e32 v94, 16, v102
	v_and_b32_e32 v95, 0xffff0000, v102
	v_lshlrev_b32_e32 v98, 16, v103
	v_and_b32_e32 v99, 0xffff0000, v103
	v_lshlrev_b32_e32 v86, 16, v106
	v_and_b32_e32 v87, 0xffff0000, v106
	v_lshlrev_b32_e32 v88, 16, v107
	v_and_b32_e32 v89, 0xffff0000, v107
	v_lshlrev_b32_e32 v102, 16, v114
	v_and_b32_e32 v103, 0xffff0000, v114
	v_lshlrev_b32_e32 v106, 16, v115
	v_and_b32_e32 v107, 0xffff0000, v115
	v_mov_b32_e32 v14, v2
	v_mov_b32_dpp v18, v152 row_shr:2 row_mask:0xf bank_mask:0xf
	v_mov_b32_e32 v15, v2
	v_mov_b32_dpp v19, v153 row_shr:2 row_mask:0xf bank_mask:0xf
	v_mov_b32_e32 v192, v2
	v_mov_b32_dpp v194, v154 row_shr:2 row_mask:0xf bank_mask:0xf
	v_mov_b32_e32 v193, v2
	v_mov_b32_dpp v195, v155 row_shr:2 row_mask:0xf bank_mask:0xf
	v_lshlrev_b32_e32 v84, 16, v110
	v_and_b32_e32 v85, 0xffff0000, v110
	v_lshlrev_b32_e32 v90, 16, v111
	v_and_b32_e32 v91, 0xffff0000, v111
	v_mov_b32_dpp v14, v152 row_shr:1 row_mask:0xf bank_mask:0xf
	v_mov_b32_dpp v110, v156 row_ror:1 row_mask:0xf bank_mask:0xf bound_ctrl:1
	v_mov_b32_dpp v114, v156 row_ror:2 row_mask:0xf bank_mask:0xf bound_ctrl:1
	s_setprio 0
	v_mov_b32_dpp v15, v153 row_shr:1 row_mask:0xf bank_mask:0xf
	v_mov_b32_dpp v111, v157 row_ror:1 row_mask:0xf bank_mask:0xf bound_ctrl:1
	v_mov_b32_dpp v115, v157 row_ror:2 row_mask:0xf bank_mask:0xf bound_ctrl:1
	v_mov_b32_dpp v192, v154 row_shr:1 row_mask:0xf bank_mask:0xf
	v_mov_b32_dpp v193, v155 row_shr:1 row_mask:0xf bank_mask:0xf
	v_pk_fma_f32 v[156:157], v[98:99], v[194:195], v[106:107]
	v_pk_fma_f32 v[18:19], v[94:95], v[18:19], v[102:103]
	v_mov_b32_dpp v222, v154 row_ror:1 row_mask:0xf bank_mask:0xf bound_ctrl:1
	v_pk_fma_f32 v[14:15], v[86:87], v[14:15], v[18:19]
	v_pk_fma_f32 v[18:19], v[88:89], v[192:193], v[156:157]
	v_mov_b32_dpp v224, v154 row_ror:2 row_mask:0xf bank_mask:0xf bound_ctrl:1
	v_pk_fma_f32 v[18:19], v[154:155], v[90:91], v[18:19]
	v_add_f32_e32 v154, 1.0, v158
	v_mov_b32_dpp v223, v155 row_ror:1 row_mask:0xf bank_mask:0xf bound_ctrl:1
	v_mov_b32_dpp v225, v155 row_ror:2 row_mask:0xf bank_mask:0xf bound_ctrl:1
	v_rcp_f32_e32 v154, v154
	v_mul_f32_e32 v155, 0xbfb8aa3b, v7
	v_exp_f32_e32 v155, v155
	v_pk_fma_f32 v[14:15], v[152:153], v[84:85], v[14:15]
	v_mul_f32_e32 v6, v6, v154
	v_mov_b32_dpp v184, v152 row_ror:1 row_mask:0xf bank_mask:0xf bound_ctrl:1
	v_mov_b32_dpp v186, v152 row_ror:2 row_mask:0xf bank_mask:0xf bound_ctrl:1
	v_mov_b32_dpp v185, v153 row_ror:1 row_mask:0xf bank_mask:0xf bound_ctrl:1
	v_mov_b32_dpp v187, v153 row_ror:2 row_mask:0xf bank_mask:0xf bound_ctrl:1
	v_mul_f32_e32 v6, v14, v6
	v_add_f32_e32 v14, 1.0, v155
	v_mul_f32_e32 v152, 0xbfb8aa3b, v10
	v_mul_f32_e32 v153, 0xbfb8aa3b, v11
	v_mov_b32_dpp v114, v216 row_shr:2 row_mask:0xf bank_mask:0xf
	v_mov_b32_dpp v115, v217 row_shr:2 row_mask:0xf bank_mask:0xf
	v_rcp_f32_e32 v14, v14
	v_exp_f32_e32 v152, v152
	v_exp_f32_e32 v153, v153
; __device__ __forceinline__ unsigned cvt_pk_bf16(float lo, float hi) { unsigned r; asm volatile("v_cvt_pk_bf16_f32 %0, %1, %2" : "=v"(r) : "v"(lo), "v"(hi)); return r; }
; __device__ __forceinline__ float fexp2(float x) { return __builtin_amdgcn_exp2f(x); }
; __device__ __forceinline__ float frcp(float x) { return __builtin_amdgcn_rcpf(x); }
; __device__ __forceinline__ float dpp_shr1(float old, float src) { return __int_as_float(__builtin_amdgcn_update_dpp(__float_as_int(old), __float_as_int(src), 0x111, 0xf, 0xf, false)); }
; __device__ __forceinline__ float dpp_shr2(float old, float src) { return __int_as_float(__builtin_amdgcn_update_dpp(__float_as_int(old), __float_as_int(src), 0x112, 0xf, 0xf, false)); }
; __device__ __forceinline__ float dpp_ror1(float src) { return __int_as_float(__builtin_amdgcn_mov_dpp(__float_as_int(src), 0x121, 0xf, 0xf, true)); }
; __device__ __forceinline__ float dpp_ror2(float src) { return __int_as_float(__builtin_amdgcn_mov_dpp(__float_as_int(src), 0x122, 0xf, 0xf, true)); }
;     __device__ __forceinline__ void operator()(f32x4 (&acc)[2][2][4][2], const Unit& u, int wr, int wc, int fr, int fq) const {
;     ...
;                 for (int m = 0; m < 4; ++m) {
;                     const f32x4 zg = acc[ai][0][m][n], zv = acc[ai][1][m][n];
;                     f32x4 g1, g2, v1, v2;
; #pragma unroll
;                     for (int j = 0; j < 4; ++j) { g1[j] = dpp_shr1(pg1[j], zg[j]); g2[j] = dpp_shr2(pg2[j], zg[j]); v1[j] = dpp_shr1(pv1[j], zv[j]); v2[j] = dpp_shr2(pv2[j], zv[j]);
;                         pg1[j] = dpp_ror1(zg[j]); pg2[j] = dpp_ror2(zg[j]); pv1[j] = dpp_ror1(zv[j]); pv2[j] = dpp_ror2(zv[j]); }
;                     const f32x4 cg_ = bg + wg0 * g2 + wg1 * g1 + wg2 * zg, cv_ = bv + wv0 * v2 + wv1 * v1 + wv2 * zv;
;                     float o[4];
; #pragma unroll
;                     for (int j = 0; j < 4; ++j) o[j] = cg_[j] * frcp(1.0f + fexp2(-1.4426950409f * cg_[j])) * cv_[j];
;                     pk[m][n][0] = cvt_pk_bf16(o[0], o[1]); pk[m][n][1] = cvt_pk_bf16(o[2], o[3]);
	v_mov_b32_dpp v110, v216 row_shr:1 row_mask:0xf bank_mask:0xf
	v_mov_b32_dpp v111, v217 row_shr:1 row_mask:0xf bank_mask:0xf
	v_pk_fma_f32 v[114:115], v[100:101], v[114:115], v[150:151]
	v_mul_f32_e32 v7, v7, v14
	v_pk_fma_f32 v[110:111], v[108:109], v[110:111], v[114:115]
	v_add_f32_e32 v14, 1.0, v152
	v_pk_fma_f32 v[110:111], v[216:217], v[92:93], v[110:111]
	v_add_f32_e32 v152, 1.0, v153
	v_mul_f32_e32 v192, 0xbfb8aa3b, v110
	s_setprio 1
	v_exp_f32_e32 v192, v192
	v_rcp_f32_e32 v14, v14
	v_rcp_f32_e32 v152, v152
	v_mov_b32_dpp v186, v210 row_shr:2 row_mask:0xf bank_mask:0xf
	v_mov_b32_dpp v187, v211 row_shr:2 row_mask:0xf bank_mask:0xf
	v_mov_b32_dpp v184, v210 row_shr:1 row_mask:0xf bank_mask:0xf
	v_mov_b32_dpp v185, v211 row_shr:1 row_mask:0xf bank_mask:0xf
	v_pk_fma_f32 v[186:187], v[94:95], v[186:187], v[102:103]
	v_mov_b32_dpp v221, v159 row_ror:2 row_mask:0xf bank_mask:0xf bound_ctrl:1
	v_pk_fma_f32 v[184:185], v[86:87], v[184:185], v[186:187]
	v_add_f32_e32 v186, 1.0, v192
	v_mul_f32_e32 v10, v10, v14
	v_mul_f32_e32 v11, v11, v152
	v_rcp_f32_e32 v186, v186
	v_mul_f32_e32 v187, 0xbfb8aa3b, v111
	v_mov_b32_dpp v219, v159 row_ror:1 row_mask:0xf bank_mask:0xf bound_ctrl:1
	v_mul_f32_e32 v7, v15, v7
	v_mul_f32_e32 v10, v18, v10
	v_mul_f32_e32 v11, v19, v11
	v_mov_b32_dpp v18, v216 row_ror:2 row_mask:0xf bank_mask:0xf bound_ctrl:1
	v_mov_b32_dpp v19, v217 row_ror:2 row_mask:0xf bank_mask:0xf bound_ctrl:1
	v_mov_b32_dpp v220, v214 row_shr:2 row_mask:0xf bank_mask:0xf
	v_mov_b32_dpp v221, v215 row_shr:2 row_mask:0xf bank_mask:0xf
	v_exp_f32_e32 v187, v187
	v_cvt_pk_bf16_f32 v6, v6, v7
	v_cvt_pk_bf16_f32 v7, v10, v11
	v_mov_b32_dpp v14, v216 row_ror:1 row_mask:0xf bank_mask:0xf bound_ctrl:1
	v_mov_b32_dpp v15, v217 row_ror:1 row_mask:0xf bank_mask:0xf bound_ctrl:1
	v_mov_b32_dpp v218, v214 row_shr:1 row_mask:0xf bank_mask:0xf
	v_mov_b32_dpp v219, v215 row_shr:1 row_mask:0xf bank_mask:0xf
	v_pk_fma_f32 v[10:11], v[112:113], v[220:221], v[160:161]
	v_mov_b32_dpp v18, v208 row_shr:2 row_mask:0xf bank_mask:0xf
	v_mov_b32_dpp v19, v209 row_shr:2 row_mask:0xf bank_mask:0xf
	v_mov_b32_dpp v158, v214 row_ror:2 row_mask:0xf bank_mask:0xf bound_ctrl:1
	v_mov_b32_dpp v159, v215 row_ror:2 row_mask:0xf bank_mask:0xf bound_ctrl:1
	v_pk_fma_f32 v[10:11], v[96:97], v[218:219], v[10:11]
	v_mov_b32_dpp v14, v208 row_shr:1 row_mask:0xf bank_mask:0xf
	v_mov_b32_dpp v15, v209 row_shr:1 row_mask:0xf bank_mask:0xf
	s_setprio 0
	v_pk_fma_f32 v[18:19], v[100:101], v[18:19], v[150:151]
	v_mov_b32_dpp v156, v214 row_ror:1 row_mask:0xf bank_mask:0xf bound_ctrl:1
	v_mov_b32_dpp v157, v215 row_ror:1 row_mask:0xf bank_mask:0xf bound_ctrl:1
	v_pk_fma_f32 v[10:11], v[214:215], v[104:105], v[10:11]
	v_pk_fma_f32 v[184:185], v[210:211], v[84:85], v[184:185]
	v_mul_f32_e32 v110, v110, v186
	v_mov_b32_dpp v158, v206 row_shr:2 row_mask:0xf bank_mask:0xf
	v_mov_b32_dpp v159, v207 row_shr:2 row_mask:0xf bank_mask:0xf
	v_pk_fma_f32 v[14:15], v[108:109], v[14:15], v[18:19]
	v_mul_f32_e32 v110, v184, v110
	v_add_f32_e32 v184, 1.0, v187
	v_mul_f32_e32 v186, 0xbfb8aa3b, v10
	v_mov_b32_dpp v156, v206 row_shr:1 row_mask:0xf bank_mask:0xf
	v_mov_b32_dpp v157, v207 row_shr:1 row_mask:0xf bank_mask:0xf
	v_pk_fma_f32 v[158:159], v[112:113], v[158:159], v[160:161]
	v_pk_fma_f32 v[14:15], v[208:209], v[92:93], v[14:15]
	v_rcp_f32_e32 v184, v184
	v_exp_f32_e32 v186, v186
	v_mul_f32_e32 v187, 0xbfb8aa3b, v11
	v_pk_fma_f32 v[18:19], v[96:97], v[156:157], v[158:159]
	v_mul_f32_e32 v158, 0xbfb8aa3b, v14
	v_exp_f32_e32 v187, v187
	v_exp_f32_e32 v158, v158
	v_mov_b32_dpp v154, v210 row_ror:2 row_mask:0xf bank_mask:0xf bound_ctrl:1
	v_mov_b32_dpp v155, v211 row_ror:2 row_mask:0xf bank_mask:0xf bound_ctrl:1
	v_mov_b32_dpp v190, v212 row_ror:2 row_mask:0xf bank_mask:0xf bound_ctrl:1
	v_mov_b32_dpp v191, v213 row_ror:2 row_mask:0xf bank_mask:0xf bound_ctrl:1
	v_mov_b32_dpp v152, v210 row_ror:1 row_mask:0xf bank_mask:0xf bound_ctrl:1
	v_mov_b32_dpp v153, v211 row_ror:1 row_mask:0xf bank_mask:0xf bound_ctrl:1
	v_mov_b32_dpp v188, v212 row_ror:1 row_mask:0xf bank_mask:0xf bound_ctrl:1
	v_mov_b32_dpp v189, v213 row_ror:1 row_mask:0xf bank_mask:0xf bound_ctrl:1
	v_mov_b32_dpp v154, v202 row_shr:2 row_mask:0xf bank_mask:0xf
	v_mov_b32_dpp v155, v203 row_shr:2 row_mask:0xf bank_mask:0xf
	v_mov_b32_dpp v190, v204 row_shr:2 row_mask:0xf bank_mask:0xf
	v_mov_b32_dpp v191, v205 row_shr:2 row_mask:0xf bank_mask:0xf
	v_mul_f32_e32 v111, v111, v184
	v_add_f32_e32 v184, 1.0, v186
	v_mov_b32_dpp v152, v202 row_shr:1 row_mask:0xf bank_mask:0xf
	v_mov_b32_dpp v153, v203 row_shr:1 row_mask:0xf bank_mask:0xf
	v_mov_b32_dpp v188, v204 row_shr:1 row_mask:0xf bank_mask:0xf
	v_mov_b32_dpp v189, v205 row_shr:1 row_mask:0xf bank_mask:0xf
	v_pk_fma_f32 v[156:157], v[98:99], v[190:191], v[106:107]
	s_setprio 1
	v_pk_fma_f32 v[154:155], v[94:95], v[154:155], v[102:103]
	v_rcp_f32_e32 v184, v184
	v_add_f32_e32 v186, 1.0, v187
	v_pk_fma_f32 v[152:153], v[86:87], v[152:153], v[154:155]
	v_pk_fma_f32 v[154:155], v[88:89], v[188:189], v[156:157]
	v_add_f32_e32 v156, 1.0, v158
	v_mov_b32_dpp v224, v212 row_shr:2 row_mask:0xf bank_mask:0xf
	v_mov_b32_dpp v225, v213 row_shr:2 row_mask:0xf bank_mask:0xf
	v_rcp_f32_e32 v186, v186
	v_rcp_f32_e32 v156, v156
	v_mul_f32_e32 v157, 0xbfb8aa3b, v15
	v_mov_b32_dpp v222, v212 row_shr:1 row_mask:0xf bank_mask:0xf
	v_mov_b32_dpp v223, v213 row_shr:1 row_mask:0xf bank_mask:0xf
	v_pk_fma_f32 v[114:115], v[98:99], v[224:225], v[106:107]
	v_exp_f32_e32 v157, v157
	v_pk_fma_f32 v[114:115], v[88:89], v[222:223], v[114:115]
	v_mul_f32_e32 v10, v10, v184
	v_pk_fma_f32 v[114:115], v[212:213], v[90:91], v[114:115]
; __device__ __forceinline__ unsigned cvt_pk_bf16(float lo, float hi) { unsigned r; asm volatile("v_cvt_pk_bf16_f32 %0, %1, %2" : "=v"(r) : "v"(lo), "v"(hi)); return r; }
; __device__ __forceinline__ float fexp2(float x) { return __builtin_amdgcn_exp2f(x); }
; __device__ __forceinline__ float frcp(float x) { return __builtin_amdgcn_rcpf(x); }
; __device__ __forceinline__ float dpp_shr1(float old, float src) { return __int_as_float(__builtin_amdgcn_update_dpp(__float_as_int(old), __float_as_int(src), 0x111, 0xf, 0xf, false)); }
; __device__ __forceinline__ float dpp_shr2(float old, float src) { return __int_as_float(__builtin_amdgcn_update_dpp(__float_as_int(old), __float_as_int(src), 0x112, 0xf, 0xf, false)); }
; __device__ __forceinline__ float dpp_ror1(float src) { return __int_as_float(__builtin_amdgcn_mov_dpp(__float_as_int(src), 0x121, 0xf, 0xf, true)); }
; __device__ __forceinline__ float dpp_ror2(float src) { return __int_as_float(__builtin_amdgcn_mov_dpp(__float_as_int(src), 0x122, 0xf, 0xf, true)); }
;     __device__ __forceinline__ void operator()(f32x4 (&acc)[2][2][4][2], const Unit& u, int wr, int wc, int fr, int fq) const {
;     ...
;                 for (int m = 0; m < 4; ++m) {
;                     const f32x4 zg = acc[ai][0][m][n], zv = acc[ai][1][m][n];
;                     f32x4 g1, g2, v1, v2;
; #pragma unroll
;                     for (int j = 0; j < 4; ++j) { g1[j] = dpp_shr1(pg1[j], zg[j]); g2[j] = dpp_shr2(pg2[j], zg[j]); v1[j] = dpp_shr1(pv1[j], zv[j]); v2[j] = dpp_shr2(pv2[j], zv[j]);
;                         pg1[j] = dpp_ror1(zg[j]); pg2[j] = dpp_ror2(zg[j]); pv1[j] = dpp_ror1(zv[j]); pv2[j] = dpp_ror2(zv[j]); }
;                     const f32x4 cg_ = bg + wg0 * g2 + wg1 * g1 + wg2 * zg, cv_ = bv + wv0 * v2 + wv1 * v1 + wv2 * zv;
;                     float o[4];
; #pragma unroll
;                     for (int j = 0; j < 4; ++j) o[j] = cg_[j] * frcp(1.0f + fexp2(-1.4426950409f * cg_[j])) * cv_[j];
;                     pk[m][n][0] = cvt_pk_bf16(o[0], o[1]); pk[m][n][1] = cvt_pk_bf16(o[2], o[3]);
;                 }
;             }
; #pragma unroll
;             for (int m = 0; m < 4; ++m) { u32x4 w; w.x = pk[m][0][0]; w.y = pk[m][0][1]; w.z = pk[m][1][0]; w.w = pk[m][1][1];
;                 *(u32x4*)(act + (size_t)(row0 + ai * HALF + m * 16) * 2816 + f0) = w; }
	v_pk_fma_f32 v[18:19], v[206:207], v[104:105], v[18:19]
	v_mul_f32_e32 v114, v114, v10
	v_mul_f32_e32 v10, v11, v186
	v_pk_fma_f32 v[152:153], v[202:203], v[84:85], v[152:153]
	v_mul_f32_e32 v14, v14, v156
	v_mul_f32_e32 v11, v115, v10
	v_mul_f32_e32 v14, v152, v14
	v_add_f32_e32 v152, 1.0, v157
	v_mul_f32_e32 v156, 0xbfb8aa3b, v18
	v_mul_f32_e32 v157, 0xbfb8aa3b, v19
	v_mul_f32_e32 v111, v185, v111
	v_cvt_pk_bf16_f32 v10, v110, v111
	v_cvt_pk_bf16_f32 v11, v114, v11
	v_mov_b32_dpp v114, v208 row_ror:2 row_mask:0xf bank_mask:0xf bound_ctrl:1
	v_mov_b32_dpp v115, v209 row_ror:2 row_mask:0xf bank_mask:0xf bound_ctrl:1
	v_rcp_f32_e32 v152, v152
	v_exp_f32_e32 v156, v156
	v_exp_f32_e32 v157, v157
	v_mov_b32_dpp v110, v208 row_ror:1 row_mask:0xf bank_mask:0xf bound_ctrl:1
	v_mov_b32_dpp v111, v209 row_ror:1 row_mask:0xf bank_mask:0xf bound_ctrl:1
	s_setprio 0
	v_mov_b32_dpp v114, v142 row_shr:2 row_mask:0xf bank_mask:0xf
	v_mov_b32_dpp v115, v143 row_shr:2 row_mask:0xf bank_mask:0xf
	v_mov_b32_dpp v110, v142 row_shr:1 row_mask:0xf bank_mask:0xf
	v_mov_b32_dpp v111, v143 row_shr:1 row_mask:0xf bank_mask:0xf
	v_pk_fma_f32 v[114:115], v[100:101], v[114:115], v[150:151]
	v_mul_f32_e32 v15, v15, v152
	v_pk_fma_f32 v[110:111], v[108:109], v[110:111], v[114:115]
	v_add_f32_e32 v152, 1.0, v156
	v_add_f32_e32 v156, 1.0, v157
	v_pk_fma_f32 v[110:111], v[142:143], v[92:93], v[110:111]
	v_rcp_f32_e32 v152, v152
	v_rcp_f32_e32 v156, v156
	v_mul_f32_e32 v142, 0xbfb8aa3b, v110
	v_mov_b32_dpp v212, v204 row_ror:2 row_mask:0xf bank_mask:0xf bound_ctrl:1
	v_mov_b32_dpp v213, v205 row_ror:2 row_mask:0xf bank_mask:0xf bound_ctrl:1
	v_exp_f32_e32 v142, v142
	v_mov_b32_dpp v210, v204 row_ror:1 row_mask:0xf bank_mask:0xf bound_ctrl:1
	v_mov_b32_dpp v211, v205 row_ror:1 row_mask:0xf bank_mask:0xf bound_ctrl:1
	v_mov_b32_dpp v212, v138 row_shr:2 row_mask:0xf bank_mask:0xf
	v_mov_b32_dpp v213, v139 row_shr:2 row_mask:0xf bank_mask:0xf
	v_mov_b32_dpp v210, v138 row_shr:1 row_mask:0xf bank_mask:0xf
	v_mov_b32_dpp v211, v139 row_shr:1 row_mask:0xf bank_mask:0xf
	v_pk_fma_f32 v[114:115], v[98:99], v[212:213], v[106:107]
	v_mov_b32_dpp v194, v206 row_ror:2 row_mask:0xf bank_mask:0xf bound_ctrl:1
	v_mov_b32_dpp v195, v207 row_ror:2 row_mask:0xf bank_mask:0xf bound_ctrl:1
	v_pk_fma_f32 v[154:155], v[204:205], v[90:91], v[154:155]
	v_mul_f32_e32 v18, v18, v152
	v_mul_f32_e32 v19, v19, v156
	v_pk_fma_f32 v[114:115], v[88:89], v[210:211], v[114:115]
	v_mov_b32_dpp v192, v206 row_ror:1 row_mask:0xf bank_mask:0xf bound_ctrl:1
	v_mov_b32_dpp v193, v207 row_ror:1 row_mask:0xf bank_mask:0xf bound_ctrl:1
	v_mul_f32_e32 v15, v153, v15
	v_mul_f32_e32 v18, v154, v18
	v_mul_f32_e32 v19, v155, v19
	v_mov_b32_dpp v194, v140 row_shr:2 row_mask:0xf bank_mask:0xf
	v_mov_b32_dpp v195, v141 row_shr:2 row_mask:0xf bank_mask:0xf
	v_pk_fma_f32 v[114:115], v[138:139], v[90:91], v[114:115]
	v_add_f32_e32 v138, 1.0, v142
	v_mov_b32_dpp v186, v202 row_ror:2 row_mask:0xf bank_mask:0xf bound_ctrl:1
	v_mov_b32_dpp v187, v203 row_ror:2 row_mask:0xf bank_mask:0xf bound_ctrl:1
	v_cvt_pk_bf16_f32 v14, v14, v15
	s_setprio 1
	v_cvt_pk_bf16_f32 v15, v18, v19
	v_mov_b32_dpp v192, v140 row_shr:1 row_mask:0xf bank_mask:0xf
	v_mov_b32_dpp v193, v141 row_shr:1 row_mask:0xf bank_mask:0xf
	v_pk_fma_f32 v[18:19], v[112:113], v[194:195], v[160:161]
	v_rcp_f32_e32 v138, v138
	v_mul_f32_e32 v139, 0xbfb8aa3b, v111
	v_mov_b32_dpp v184, v202 row_ror:1 row_mask:0xf bank_mask:0xf bound_ctrl:1
	v_mov_b32_dpp v185, v203 row_ror:1 row_mask:0xf bank_mask:0xf bound_ctrl:1
	v_mov_b32_dpp v186, v136 row_shr:2 row_mask:0xf bank_mask:0xf
	v_mov_b32_dpp v187, v137 row_shr:2 row_mask:0xf bank_mask:0xf
	v_pk_fma_f32 v[18:19], v[96:97], v[192:193], v[18:19]
	v_exp_f32_e32 v139, v139
	v_mov_b32_dpp v184, v136 row_shr:1 row_mask:0xf bank_mask:0xf
	v_mov_b32_dpp v185, v137 row_shr:1 row_mask:0xf bank_mask:0xf
	v_pk_fma_f32 v[18:19], v[140:141], v[104:105], v[18:19]
	v_pk_fma_f32 v[140:141], v[94:95], v[186:187], v[102:103]
	v_mul_f32_e32 v110, v110, v138
	v_pk_fma_f32 v[140:141], v[86:87], v[184:185], v[140:141]
	v_mul_f32_e32 v138, 0xbfb8aa3b, v18
	v_pk_fma_f32 v[136:137], v[136:137], v[84:85], v[140:141]
	v_exp_f32_e32 v138, v138
	v_mul_f32_e32 v110, v136, v110
	v_add_f32_e32 v136, 1.0, v139
	v_rcp_f32_e32 v136, v136
	v_mul_f32_e32 v139, 0xbfb8aa3b, v19
	v_exp_f32_e32 v139, v139
	v_mov_b32_dpp v142, v132 row_ror:1 row_mask:0xf bank_mask:0xf bound_ctrl:1
	v_mul_f32_e32 v111, v111, v136
	v_add_f32_e32 v136, 1.0, v138
	v_rcp_f32_e32 v136, v136
	v_add_f32_e32 v138, 1.0, v139
	v_rcp_f32_e32 v138, v138
	v_mul_f32_e32 v111, v137, v111
	v_mul_f32_e32 v18, v18, v136
	v_mul_f32_e32 v114, v114, v18
	v_mul_f32_e32 v18, v19, v138
	v_mul_f32_e32 v19, v115, v18
	v_cvt_pk_bf16_f32 v18, v110, v111
	s_setprio 0
	v_mov_b64_e32 v[110:111], s[16:17]
	v_cvt_pk_bf16_f32 v19, v114, v19
	v_mad_i64_i32 v[114:115], s[18:19], v176, s22, v[110:111]
	v_lshl_add_u64 v[114:115], v[114:115], 0, v[68:69]
	global_store_dwordx4 v[114:115], v[4:7], off
	v_mov_b32_e32 v136, v2
	v_mov_b32_e32 v137, v2
	v_mad_i64_i32 v[4:5], s[18:19], v249, s22, v[110:111]
	v_lshl_add_u64 v[4:5], v[4:5], 0, v[68:69]
	global_store_dwordx4 v[4:5], v[8:11], off
	v_mad_i64_i32 v[4:5], s[18:19], v250, s22, v[110:111]
	v_lshl_add_u64 v[4:5], v[4:5], 0, v[68:69]
	global_store_dwordx4 v[4:5], v[12:15], off
	v_mad_i64_i32 v[4:5], s[18:19], v251, s22, v[110:111]
	v_lshl_add_u64 v[4:5], v[4:5], 0, v[68:69]
	v_mov_b32_e32 v6, v2
	v_mov_b32_e32 v7, v2
	global_store_dwordx4 v[4:5], v[16:19], off
	v_mov_b32_e32 v4, v2
	v_mov_b32_dpp v6, v134 row_shr:2 row_mask:0xf bank_mask:0xf
	v_mov_b32_e32 v5, v2
; __device__ __forceinline__ unsigned cvt_pk_bf16(float lo, float hi) { unsigned r; asm volatile("v_cvt_pk_bf16_f32 %0, %1, %2" : "=v"(r) : "v"(lo), "v"(hi)); return r; }
; __device__ __forceinline__ float fexp2(float x) { return __builtin_amdgcn_exp2f(x); }
; __device__ __forceinline__ float frcp(float x) { return __builtin_amdgcn_rcpf(x); }
; __device__ __forceinline__ float dpp_shr1(float old, float src) { return __int_as_float(__builtin_amdgcn_update_dpp(__float_as_int(old), __float_as_int(src), 0x111, 0xf, 0xf, false)); }
; __device__ __forceinline__ float dpp_shr2(float old, float src) { return __int_as_float(__builtin_amdgcn_update_dpp(__float_as_int(old), __float_as_int(src), 0x112, 0xf, 0xf, false)); }
; __device__ __forceinline__ float dpp_ror1(float src) { return __int_as_float(__builtin_amdgcn_mov_dpp(__float_as_int(src), 0x121, 0xf, 0xf, true)); }
; __device__ __forceinline__ float dpp_ror2(float src) { return __int_as_float(__builtin_amdgcn_mov_dpp(__float_as_int(src), 0x122, 0xf, 0xf, true)); }
;     __device__ __forceinline__ void operator()(f32x4 (&acc)[2][2][4][2], const Unit& u, int wr, int wc, int fr, int fq) const {
;     ...
;                 for (int m = 0; m < 4; ++m) {
;                     const f32x4 zg = acc[ai][0][m][n], zv = acc[ai][1][m][n];
;                     f32x4 g1, g2, v1, v2;
; #pragma unroll
;                     for (int j = 0; j < 4; ++j) { g1[j] = dpp_shr1(pg1[j], zg[j]); g2[j] = dpp_shr2(pg2[j], zg[j]); v1[j] = dpp_shr1(pv1[j], zv[j]); v2[j] = dpp_shr2(pv2[j], zv[j]);
;                         pg1[j] = dpp_ror1(zg[j]); pg2[j] = dpp_ror2(zg[j]); pv1[j] = dpp_ror1(zv[j]); pv2[j] = dpp_ror2(zv[j]); }
;                     const f32x4 cg_ = bg + wg0 * g2 + wg1 * g1 + wg2 * zg, cv_ = bv + wv0 * v2 + wv1 * v1 + wv2 * zv;
;                     float o[4];
; #pragma unroll
;                     for (int j = 0; j < 4; ++j) o[j] = cg_[j] * frcp(1.0f + fexp2(-1.4426950409f * cg_[j])) * cv_[j];
;                     pk[m][n][0] = cvt_pk_bf16(o[0], o[1]); pk[m][n][1] = cvt_pk_bf16(o[2], o[3]);
	v_mov_b32_dpp v7, v135 row_shr:2 row_mask:0xf bank_mask:0xf
	v_mov_b32_dpp v4, v134 row_shr:1 row_mask:0xf bank_mask:0xf
	v_mov_b32_dpp v5, v135 row_shr:1 row_mask:0xf bank_mask:0xf
	v_mov_b32_e32 v114, v2
	v_mov_b32_dpp v136, v132 row_shr:2 row_mask:0xf bank_mask:0xf
	v_mov_b32_e32 v115, v2
	v_mov_b32_dpp v137, v133 row_shr:2 row_mask:0xf bank_mask:0xf
	v_pk_fma_f32 v[6:7], v[50:51], v[6:7], v[62:63]
	v_mov_b32_dpp v114, v132 row_shr:1 row_mask:0xf bank_mask:0xf
	v_mov_b32_dpp v115, v133 row_shr:1 row_mask:0xf bank_mask:0xf
	v_pk_fma_f32 v[136:137], v[58:59], v[136:137], v[66:67]
	v_pk_fma_f32 v[4:5], v[54:55], v[4:5], v[6:7]
	v_pk_fma_f32 v[6:7], v[48:49], v[114:115], v[136:137]
	v_pk_fma_f32 v[4:5], v[134:135], v[44:45], v[4:5]
	v_mov_b32_dpp v152, v132 row_ror:2 row_mask:0xf bank_mask:0xf bound_ctrl:1
	v_pk_fma_f32 v[6:7], v[132:133], v[52:53], v[6:7]
	v_mul_f32_e32 v132, 0xbfb8aa3b, v4
	v_exp_f32_e32 v132, v132
	s_setprio 1
	v_mov_b32_e32 v10, v2
	v_mov_b32_e32 v11, v2
	v_mov_b32_e32 v140, v2
	v_mov_b32_e32 v141, v2
	v_mov_b32_e32 v8, v2
	v_mov_b32_dpp v10, v124 row_shr:2 row_mask:0xf bank_mask:0xf
	v_mov_b32_e32 v9, v2
	v_mov_b32_dpp v11, v125 row_shr:2 row_mask:0xf bank_mask:0xf
	v_mov_b32_e32 v138, v2
	v_mov_b32_dpp v140, v126 row_shr:2 row_mask:0xf bank_mask:0xf
	v_mov_b32_e32 v139, v2
	v_mov_b32_dpp v141, v127 row_shr:2 row_mask:0xf bank_mask:0xf
	v_mov_b32_dpp v8, v124 row_shr:1 row_mask:0xf bank_mask:0xf
	v_mov_b32_dpp v9, v125 row_shr:1 row_mask:0xf bank_mask:0xf
	v_mov_b32_dpp v138, v126 row_shr:1 row_mask:0xf bank_mask:0xf
	v_mov_b32_dpp v139, v127 row_shr:1 row_mask:0xf bank_mask:0xf
	v_pk_fma_f32 v[114:115], v[56:57], v[140:141], v[64:65]
	v_pk_fma_f32 v[10:11], v[46:47], v[10:11], v[60:61]
	v_mov_b32_dpp v14, v134 row_ror:2 row_mask:0xf bank_mask:0xf bound_ctrl:1
	v_pk_fma_f32 v[8:9], v[38:39], v[8:9], v[10:11]
	v_pk_fma_f32 v[10:11], v[40:41], v[138:139], v[114:115]
	v_add_f32_e32 v114, 1.0, v132
	v_rcp_f32_e32 v114, v114
	v_mul_f32_e32 v115, 0xbfb8aa3b, v5
	v_exp_f32_e32 v115, v115
	v_mov_b32_dpp v15, v135 row_ror:2 row_mask:0xf bank_mask:0xf bound_ctrl:1
	v_mov_b32_dpp v12, v134 row_ror:1 row_mask:0xf bank_mask:0xf bound_ctrl:1
	v_mov_b32_dpp v13, v135 row_ror:1 row_mask:0xf bank_mask:0xf bound_ctrl:1
	v_mov_b32_dpp v14, v182 row_shr:2 row_mask:0xf bank_mask:0xf
	v_mov_b32_dpp v15, v183 row_shr:2 row_mask:0xf bank_mask:0xf
	v_pk_fma_f32 v[8:9], v[124:125], v[36:37], v[8:9]
	v_mul_f32_e32 v4, v4, v114
	v_mov_b32_dpp v12, v182 row_shr:1 row_mask:0xf bank_mask:0xf
	v_mov_b32_dpp v13, v183 row_shr:1 row_mask:0xf bank_mask:0xf
	v_pk_fma_f32 v[14:15], v[50:51], v[14:15], v[62:63]
	v_mul_f32_e32 v4, v8, v4
	v_add_f32_e32 v8, 1.0, v115
	v_mul_f32_e32 v114, 0xbfb8aa3b, v6
	v_pk_fma_f32 v[12:13], v[54:55], v[12:13], v[14:15]
	v_rcp_f32_e32 v8, v8
	v_exp_f32_e32 v114, v114
	v_pk_fma_f32 v[12:13], v[182:183], v[44:45], v[12:13]
	s_setprio 0
	v_mov_b32_dpp v18, v124 row_ror:2 row_mask:0xf bank_mask:0xf bound_ctrl:1
	v_mul_f32_e32 v138, 0xbfb8aa3b, v12
	v_exp_f32_e32 v138, v138
	v_mov_b32_dpp v19, v125 row_ror:2 row_mask:0xf bank_mask:0xf bound_ctrl:1
	v_mov_b32_dpp v16, v124 row_ror:1 row_mask:0xf bank_mask:0xf bound_ctrl:1
	v_mov_b32_dpp v17, v125 row_ror:1 row_mask:0xf bank_mask:0xf bound_ctrl:1
	v_mul_f32_e32 v5, v5, v8
	v_add_f32_e32 v8, 1.0, v114
	v_mov_b32_dpp v18, v162 row_shr:2 row_mask:0xf bank_mask:0xf
	v_mov_b32_dpp v19, v163 row_shr:2 row_mask:0xf bank_mask:0xf
	v_rcp_f32_e32 v8, v8
	v_mov_b32_dpp v16, v162 row_shr:1 row_mask:0xf bank_mask:0xf
	v_mov_b32_dpp v17, v163 row_shr:1 row_mask:0xf bank_mask:0xf
	v_pk_fma_f32 v[18:19], v[46:47], v[18:19], v[60:61]
	v_mov_b32_dpp v153, v133 row_ror:2 row_mask:0xf bank_mask:0xf bound_ctrl:1
	v_pk_fma_f32 v[16:17], v[38:39], v[16:17], v[18:19]
	v_add_f32_e32 v18, 1.0, v138
	v_rcp_f32_e32 v18, v18
	v_mul_f32_e32 v19, 0xbfb8aa3b, v13
	v_mov_b32_dpp v143, v133 row_ror:1 row_mask:0xf bank_mask:0xf bound_ctrl:1
	v_mov_b32_dpp v152, v180 row_shr:2 row_mask:0xf bank_mask:0xf
	v_mov_b32_dpp v153, v181 row_shr:2 row_mask:0xf bank_mask:0xf
	v_exp_f32_e32 v19, v19
	v_mul_f32_e32 v115, 0xbfb8aa3b, v7
	v_mul_f32_e32 v5, v9, v5
	v_mul_f32_e32 v6, v6, v8
	v_mov_b32_dpp v142, v180 row_shr:1 row_mask:0xf bank_mask:0xf
	v_mov_b32_dpp v143, v181 row_shr:1 row_mask:0xf bank_mask:0xf
	v_pk_fma_f32 v[8:9], v[58:59], v[152:153], v[66:67]
	v_exp_f32_e32 v115, v115
	v_pk_fma_f32 v[8:9], v[48:49], v[142:143], v[8:9]
	v_pk_fma_f32 v[16:17], v[162:163], v[36:37], v[16:17]
	v_pk_fma_f32 v[8:9], v[180:181], v[52:53], v[8:9]
	v_mul_f32_e32 v12, v12, v18
	v_mul_f32_e32 v12, v16, v12
	v_add_f32_e32 v16, 1.0, v19
	v_mul_f32_e32 v18, 0xbfb8aa3b, v8
	v_rcp_f32_e32 v16, v16
	v_exp_f32_e32 v18, v18
	v_mul_f32_e32 v19, 0xbfb8aa3b, v9
	v_add_f32_e32 v114, 1.0, v115
	v_exp_f32_e32 v19, v19
	s_setprio 1
	v_rcp_f32_e32 v114, v114
	v_mul_f32_e32 v13, v13, v16
	v_add_f32_e32 v16, 1.0, v18
	v_mov_b32_dpp v156, v126 row_ror:2 row_mask:0xf bank_mask:0xf bound_ctrl:1
	v_mov_b32_dpp v157, v127 row_ror:2 row_mask:0xf bank_mask:0xf bound_ctrl:1
	v_rcp_f32_e32 v16, v16
	v_add_f32_e32 v18, 1.0, v19
	v_mov_b32_dpp v154, v126 row_ror:1 row_mask:0xf bank_mask:0xf bound_ctrl:1
	v_mov_b32_dpp v155, v127 row_ror:1 row_mask:0xf bank_mask:0xf bound_ctrl:1
	v_pk_fma_f32 v[10:11], v[126:127], v[42:43], v[10:11]
	v_mul_f32_e32 v7, v7, v114
	v_mov_b32_dpp v156, v178 row_shr:2 row_mask:0xf bank_mask:0xf
	v_mov_b32_dpp v157, v179 row_shr:2 row_mask:0xf bank_mask:0xf
	v_rcp_f32_e32 v18, v18
	v_mul_f32_e32 v6, v10, v6
	v_mul_f32_e32 v7, v11, v7
	v_mov_b32_dpp v10, v182 row_ror:2 row_mask:0xf bank_mask:0xf bound_ctrl:1
; __device__ __forceinline__ unsigned cvt_pk_bf16(float lo, float hi) { unsigned r; asm volatile("v_cvt_pk_bf16_f32 %0, %1, %2" : "=v"(r) : "v"(lo), "v"(hi)); return r; }
; __device__ __forceinline__ float fexp2(float x) { return __builtin_amdgcn_exp2f(x); }
; __device__ __forceinline__ float frcp(float x) { return __builtin_amdgcn_rcpf(x); }
; __device__ __forceinline__ float dpp_shr1(float old, float src) { return __int_as_float(__builtin_amdgcn_update_dpp(__float_as_int(old), __float_as_int(src), 0x111, 0xf, 0xf, false)); }
; __device__ __forceinline__ float dpp_shr2(float old, float src) { return __int_as_float(__builtin_amdgcn_update_dpp(__float_as_int(old), __float_as_int(src), 0x112, 0xf, 0xf, false)); }
; __device__ __forceinline__ float dpp_ror1(float src) { return __int_as_float(__builtin_amdgcn_mov_dpp(__float_as_int(src), 0x121, 0xf, 0xf, true)); }
; __device__ __forceinline__ float dpp_ror2(float src) { return __int_as_float(__builtin_amdgcn_mov_dpp(__float_as_int(src), 0x122, 0xf, 0xf, true)); }
;     __device__ __forceinline__ void operator()(f32x4 (&acc)[2][2][4][2], const Unit& u, int wr, int wc, int fr, int fq) const {
;     ...
;                 for (int m = 0; m < 4; ++m) {
;                     const f32x4 zg = acc[ai][0][m][n], zv = acc[ai][1][m][n];
;                     f32x4 g1, g2, v1, v2;
; #pragma unroll
;                     for (int j = 0; j < 4; ++j) { g1[j] = dpp_shr1(pg1[j], zg[j]); g2[j] = dpp_shr2(pg2[j], zg[j]); v1[j] = dpp_shr1(pv1[j], zv[j]); v2[j] = dpp_shr2(pv2[j], zv[j]);
;                         pg1[j] = dpp_ror1(zg[j]); pg2[j] = dpp_ror2(zg[j]); pv1[j] = dpp_ror1(zv[j]); pv2[j] = dpp_ror2(zv[j]); }
;                     const f32x4 cg_ = bg + wg0 * g2 + wg1 * g1 + wg2 * zg, cv_ = bv + wv0 * v2 + wv1 * v1 + wv2 * zv;
;                     float o[4];
; #pragma unroll
;                     for (int j = 0; j < 4; ++j) o[j] = cg_[j] * frcp(1.0f + fexp2(-1.4426950409f * cg_[j])) * cv_[j];
;                     pk[m][n][0] = cvt_pk_bf16(o[0], o[1]); pk[m][n][1] = cvt_pk_bf16(o[2], o[3]);
	v_mov_b32_dpp v11, v183 row_ror:2 row_mask:0xf bank_mask:0xf bound_ctrl:1
	v_mov_b32_dpp v154, v178 row_shr:1 row_mask:0xf bank_mask:0xf
	v_mov_b32_dpp v155, v179 row_shr:1 row_mask:0xf bank_mask:0xf
	v_pk_fma_f32 v[14:15], v[56:57], v[156:157], v[64:65]
	v_cvt_pk_bf16_f32 v4, v4, v5
	v_cvt_pk_bf16_f32 v5, v6, v7
	v_mov_b32_dpp v6, v182 row_ror:1 row_mask:0xf bank_mask:0xf bound_ctrl:1
	v_mov_b32_dpp v7, v183 row_ror:1 row_mask:0xf bank_mask:0xf bound_ctrl:1
	v_pk_fma_f32 v[14:15], v[40:41], v[154:155], v[14:15]
	v_mov_b32_dpp v10, v148 row_shr:2 row_mask:0xf bank_mask:0xf
	v_mov_b32_dpp v11, v149 row_shr:2 row_mask:0xf bank_mask:0xf
	v_mov_b32_dpp v132, v180 row_ror:2 row_mask:0xf bank_mask:0xf bound_ctrl:1
	v_mov_b32_dpp v133, v181 row_ror:2 row_mask:0xf bank_mask:0xf bound_ctrl:1
	v_pk_fma_f32 v[14:15], v[178:179], v[42:43], v[14:15]
	v_mul_f32_e32 v8, v8, v16
	v_mov_b32_dpp v6, v148 row_shr:1 row_mask:0xf bank_mask:0xf
	v_mov_b32_dpp v7, v149 row_shr:1 row_mask:0xf bank_mask:0xf
	v_pk_fma_f32 v[10:11], v[50:51], v[10:11], v[62:63]
	v_mov_b32_dpp v126, v180 row_ror:1 row_mask:0xf bank_mask:0xf bound_ctrl:1
	s_setprio 0
	v_mov_b32_dpp v127, v181 row_ror:1 row_mask:0xf bank_mask:0xf bound_ctrl:1
	v_mul_f32_e32 v13, v17, v13
	v_mul_f32_e32 v14, v14, v8
	v_mul_f32_e32 v8, v9, v18
	v_mov_b32_dpp v132, v146 row_shr:2 row_mask:0xf bank_mask:0xf
	v_mov_b32_dpp v133, v147 row_shr:2 row_mask:0xf bank_mask:0xf
	v_pk_fma_f32 v[6:7], v[54:55], v[6:7], v[10:11]
	v_mul_f32_e32 v9, v15, v8
	v_cvt_pk_bf16_f32 v8, v12, v13
	v_mov_b32_dpp v126, v146 row_shr:1 row_mask:0xf bank_mask:0xf
	v_mov_b32_dpp v127, v147 row_shr:1 row_mask:0xf bank_mask:0xf
	v_pk_fma_f32 v[12:13], v[58:59], v[132:133], v[66:67]
	v_pk_fma_f32 v[6:7], v[148:149], v[44:45], v[6:7]
	v_pk_fma_f32 v[10:11], v[48:49], v[126:127], v[12:13]
	v_mul_f32_e32 v126, 0xbfb8aa3b, v6
	v_exp_f32_e32 v126, v126
	v_mov_b32_dpp v124, v162 row_ror:2 row_mask:0xf bank_mask:0xf bound_ctrl:1
	v_mov_b32_dpp v125, v163 row_ror:2 row_mask:0xf bank_mask:0xf bound_ctrl:1
	v_mov_b32_dpp v114, v162 row_ror:1 row_mask:0xf bank_mask:0xf bound_ctrl:1
	v_mov_b32_dpp v115, v163 row_ror:1 row_mask:0xf bank_mask:0xf bound_ctrl:1
	v_mov_b32_dpp v124, v122 row_shr:2 row_mask:0xf bank_mask:0xf
	v_mov_b32_dpp v125, v123 row_shr:2 row_mask:0xf bank_mask:0xf
	v_mov_b32_dpp v114, v122 row_shr:1 row_mask:0xf bank_mask:0xf
	v_mov_b32_dpp v115, v123 row_shr:1 row_mask:0xf bank_mask:0xf
	v_pk_fma_f32 v[124:125], v[46:47], v[124:125], v[60:61]
	v_pk_fma_f32 v[10:11], v[146:147], v[52:53], v[10:11]
	v_pk_fma_f32 v[114:115], v[38:39], v[114:115], v[124:125]
	v_add_f32_e32 v124, 1.0, v126
	v_rcp_f32_e32 v124, v124
	v_mul_f32_e32 v125, 0xbfb8aa3b, v7
	v_exp_f32_e32 v125, v125
	v_pk_fma_f32 v[114:115], v[122:123], v[36:37], v[114:115]
	v_mul_f32_e32 v6, v6, v124
	v_mov_b32_dpp v18, v122 row_ror:1 row_mask:0xf bank_mask:0xf bound_ctrl:1
	v_mov_b32_dpp v138, v122 row_ror:2 row_mask:0xf bank_mask:0xf bound_ctrl:1
	v_mov_b32_dpp v19, v123 row_ror:1 row_mask:0xf bank_mask:0xf bound_ctrl:1
	v_mov_b32_dpp v139, v123 row_ror:2 row_mask:0xf bank_mask:0xf bound_ctrl:1
	v_mul_f32_e32 v6, v114, v6
	v_add_f32_e32 v114, 1.0, v125
	v_mul_f32_e32 v122, 0xbfb8aa3b, v10
	s_setprio 1
	v_mul_f32_e32 v123, 0xbfb8aa3b, v11
	v_rcp_f32_e32 v114, v114
	v_exp_f32_e32 v122, v122
	v_exp_f32_e32 v123, v123
	v_mov_b32_dpp v136, v178 row_ror:2 row_mask:0xf bank_mask:0xf bound_ctrl:1
	v_mul_f32_e32 v7, v7, v114
	v_add_f32_e32 v114, 1.0, v122
	v_add_f32_e32 v122, 1.0, v123
	v_mov_b32_dpp v137, v179 row_ror:2 row_mask:0xf bank_mask:0xf bound_ctrl:1
	v_rcp_f32_e32 v114, v114
	v_rcp_f32_e32 v122, v122
	v_mov_b32_dpp v134, v178 row_ror:1 row_mask:0xf bank_mask:0xf bound_ctrl:1
	v_mov_b32_dpp v135, v179 row_ror:1 row_mask:0xf bank_mask:0xf bound_ctrl:1
	v_mov_b32_dpp v136, v144 row_shr:2 row_mask:0xf bank_mask:0xf
	v_mov_b32_dpp v137, v145 row_shr:2 row_mask:0xf bank_mask:0xf
	v_mov_b32_dpp v134, v144 row_shr:1 row_mask:0xf bank_mask:0xf
	v_mov_b32_dpp v135, v145 row_shr:1 row_mask:0xf bank_mask:0xf
	v_pk_fma_f32 v[12:13], v[56:57], v[136:137], v[64:65]
	v_mov_b32_dpp v16, v148 row_ror:2 row_mask:0xf bank_mask:0xf bound_ctrl:1
	v_pk_fma_f32 v[12:13], v[40:41], v[134:135], v[12:13]
	v_mov_b32_dpp v17, v149 row_ror:2 row_mask:0xf bank_mask:0xf bound_ctrl:1
	v_pk_fma_f32 v[12:13], v[144:145], v[42:43], v[12:13]
	v_mul_f32_e32 v10, v10, v114
	v_mul_f32_e32 v11, v11, v122
	v_cvt_pk_bf16_f32 v9, v14, v9
	v_mov_b32_dpp v14, v148 row_ror:1 row_mask:0xf bank_mask:0xf bound_ctrl:1
	v_mov_b32_dpp v15, v149 row_ror:1 row_mask:0xf bank_mask:0xf bound_ctrl:1
	v_mul_f32_e32 v10, v12, v10
	v_mul_f32_e32 v11, v13, v11
	v_mov_b32_dpp v16, v120 row_shr:2 row_mask:0xf bank_mask:0xf
	v_mov_b32_dpp v17, v121 row_shr:2 row_mask:0xf bank_mask:0xf
	v_mul_f32_e32 v7, v115, v7
	v_cvt_pk_bf16_f32 v12, v6, v7
	v_cvt_pk_bf16_f32 v13, v10, v11
	v_mov_b32_dpp v14, v120 row_shr:1 row_mask:0xf bank_mask:0xf
	v_mov_b32_dpp v15, v121 row_shr:1 row_mask:0xf bank_mask:0xf
	s_setprio 0
	v_pk_fma_f32 v[10:11], v[50:51], v[16:17], v[62:63]
	v_mov_b32_dpp v138, v76 row_shr:2 row_mask:0xf bank_mask:0xf
	v_pk_fma_f32 v[10:11], v[54:55], v[14:15], v[10:11]
	v_mov_b32_dpp v139, v77 row_shr:2 row_mask:0xf bank_mask:0xf
	v_pk_fma_f32 v[10:11], v[120:121], v[44:45], v[10:11]
	v_mov_b32_dpp v18, v76 row_shr:1 row_mask:0xf bank_mask:0xf
	v_mul_f32_e32 v44, 0xbfb8aa3b, v10
	v_exp_f32_e32 v44, v44
	v_mov_b32_dpp v19, v77 row_shr:1 row_mask:0xf bank_mask:0xf
	v_pk_fma_f32 v[16:17], v[46:47], v[138:139], v[60:61]
	v_mov_b32_dpp v142, v146 row_ror:2 row_mask:0xf bank_mask:0xf bound_ctrl:1
	v_pk_fma_f32 v[16:17], v[38:39], v[18:19], v[16:17]
; __device__ __forceinline__ unsigned cvt_pk_bf16(float lo, float hi) { unsigned r; asm volatile("v_cvt_pk_bf16_f32 %0, %1, %2" : "=v"(r) : "v"(lo), "v"(hi)); return r; }
; __device__ __forceinline__ float fexp2(float x) { return __builtin_amdgcn_exp2f(x); }
; __device__ __forceinline__ float frcp(float x) { return __builtin_amdgcn_rcpf(x); }
; __device__ __forceinline__ float dpp_shr1(float old, float src) { return __int_as_float(__builtin_amdgcn_update_dpp(__float_as_int(old), __float_as_int(src), 0x111, 0xf, 0xf, false)); }
; __device__ __forceinline__ float dpp_shr2(float old, float src) { return __int_as_float(__builtin_amdgcn_update_dpp(__float_as_int(old), __float_as_int(src), 0x112, 0xf, 0xf, false)); }
; __device__ __forceinline__ float dpp_ror1(float src) { return __int_as_float(__builtin_amdgcn_mov_dpp(__float_as_int(src), 0x121, 0xf, 0xf, true)); }
; __device__ __forceinline__ float dpp_ror2(float src) { return __int_as_float(__builtin_amdgcn_mov_dpp(__float_as_int(src), 0x122, 0xf, 0xf, true)); }
;     __device__ __forceinline__ void operator()(f32x4 (&acc)[2][2][4][2], const Unit& u, int wr, int wc, int fr, int fq) const {
;     ...
;                 const f32x4 wg0 = CQ4(0, 0), wg1 = CQ4(0, 1), wg2 = CQ4(0, 2), bg = CQ4(0, 3);
;                 const f32x4 wv0 = CQ4(1, 0), wv1 = CQ4(1, 1), wv2 = CQ4(1, 2), bv = CQ4(1, 3);
;     ...
;                 for (int m = 0; m < 4; ++m) {
;                     const f32x4 zg = acc[ai][0][m][n], zv = acc[ai][1][m][n];
;                     f32x4 g1, g2, v1, v2;
; #pragma unroll
;                     for (int j = 0; j < 4; ++j) { g1[j] = dpp_shr1(pg1[j], zg[j]); g2[j] = dpp_shr2(pg2[j], zg[j]); v1[j] = dpp_shr1(pv1[j], zv[j]); v2[j] = dpp_shr2(pv2[j], zv[j]);
;                         pg1[j] = dpp_ror1(zg[j]); pg2[j] = dpp_ror2(zg[j]); pv1[j] = dpp_ror1(zv[j]); pv2[j] = dpp_ror2(zv[j]); }
;                     const f32x4 cg_ = bg + wg0 * g2 + wg1 * g1 + wg2 * zg, cv_ = bv + wv0 * v2 + wv1 * v1 + wv2 * zv;
;                     float o[4];
; #pragma unroll
;                     for (int j = 0; j < 4; ++j) o[j] = cg_[j] * frcp(1.0f + fexp2(-1.4426950409f * cg_[j])) * cv_[j];
;                     pk[m][n][0] = cvt_pk_bf16(o[0], o[1]); pk[m][n][1] = cvt_pk_bf16(o[2], o[3]);
	v_add_f32_e32 v18, 1.0, v44
	v_mov_b32_dpp v143, v147 row_ror:2 row_mask:0xf bank_mask:0xf bound_ctrl:1
	v_rcp_f32_e32 v18, v18
	v_mul_f32_e32 v19, 0xbfb8aa3b, v11
	v_mov_b32_dpp v140, v146 row_ror:1 row_mask:0xf bank_mask:0xf bound_ctrl:1
	v_mov_b32_dpp v141, v147 row_ror:1 row_mask:0xf bank_mask:0xf bound_ctrl:1
	v_mov_b32_dpp v142, v82 row_shr:2 row_mask:0xf bank_mask:0xf
	v_mov_b32_dpp v143, v83 row_shr:2 row_mask:0xf bank_mask:0xf
	v_exp_f32_e32 v19, v19
	v_mov_b32_dpp v140, v82 row_shr:1 row_mask:0xf bank_mask:0xf
	v_mov_b32_dpp v141, v83 row_shr:1 row_mask:0xf bank_mask:0xf
	v_pk_fma_f32 v[6:7], v[58:59], v[142:143], v[66:67]
	v_pk_fma_f32 v[16:17], v[76:77], v[36:37], v[16:17]
	v_pk_fma_f32 v[6:7], v[48:49], v[140:141], v[6:7]
	v_mul_f32_e32 v10, v10, v18
	v_pk_fma_f32 v[6:7], v[82:83], v[52:53], v[6:7]
	v_mul_f32_e32 v10, v16, v10
	v_add_f32_e32 v16, 1.0, v19
	v_mul_f32_e32 v18, 0xbfb8aa3b, v6
	v_mul_f32_e32 v19, 0xbfb8aa3b, v7
	v_rcp_f32_e32 v16, v16
	v_exp_f32_e32 v18, v18
	v_exp_f32_e32 v19, v19
	v_mov_b32_dpp v154, v144 row_ror:2 row_mask:0xf bank_mask:0xf bound_ctrl:1
	v_mul_f32_e32 v11, v11, v16
	v_add_f32_e32 v16, 1.0, v18
	v_add_f32_e32 v18, 1.0, v19
	v_mov_b32_dpp v155, v145 row_ror:2 row_mask:0xf bank_mask:0xf bound_ctrl:1
	v_rcp_f32_e32 v16, v16
	v_rcp_f32_e32 v18, v18
	s_setprio 1
	v_mov_b32_dpp v152, v144 row_ror:1 row_mask:0xf bank_mask:0xf bound_ctrl:1
	v_mov_b32_dpp v153, v145 row_ror:1 row_mask:0xf bank_mask:0xf bound_ctrl:1
	v_mov_b32_dpp v154, v78 row_shr:2 row_mask:0xf bank_mask:0xf
	v_mov_b32_dpp v155, v79 row_shr:2 row_mask:0xf bank_mask:0xf
	v_mov_b32_dpp v152, v78 row_shr:1 row_mask:0xf bank_mask:0xf
	v_mov_b32_dpp v153, v79 row_shr:1 row_mask:0xf bank_mask:0xf
	v_pk_fma_f32 v[14:15], v[56:57], v[154:155], v[64:65]
	v_mul_f32_e32 v11, v17, v11
	v_pk_fma_f32 v[14:15], v[40:41], v[152:153], v[14:15]
	v_mul_f32_e32 v6, v6, v16
	v_pk_fma_f32 v[14:15], v[78:79], v[42:43], v[14:15]
	v_mul_f32_e32 v7, v7, v18
	v_mul_f32_e32 v6, v14, v6
	v_mul_f32_e32 v7, v15, v7
	v_cvt_pk_bf16_f32 v16, v10, v11
	v_mov_b32_e32 v10, v2
	v_mov_b32_e32 v11, v2
	v_cvt_pk_bf16_f32 v17, v6, v7
	v_mov_b32_e32 v6, v2
	v_mov_b32_dpp v10, v130 row_shr:2 row_mask:0xf bank_mask:0xf
	v_mov_b32_e32 v7, v2
	v_mov_b32_dpp v11, v131 row_shr:2 row_mask:0xf bank_mask:0xf
	v_mov_b32_dpp v6, v130 row_shr:1 row_mask:0xf bank_mask:0xf
	v_mov_b32_dpp v7, v131 row_shr:1 row_mask:0xf bank_mask:0xf
	v_mov_b32_e32 v46, v2
	v_mov_b32_e32 v47, v2
	v_pk_fma_f32 v[10:11], v[100:101], v[10:11], v[150:151]
	v_mov_b32_e32 v44, v2
	v_mov_b32_dpp v46, v128 row_shr:2 row_mask:0xf bank_mask:0xf
	v_mov_b32_e32 v45, v2
	v_mov_b32_dpp v47, v129 row_shr:2 row_mask:0xf bank_mask:0xf
	v_pk_fma_f32 v[6:7], v[108:109], v[6:7], v[10:11]
	v_mov_b32_dpp v44, v128 row_shr:1 row_mask:0xf bank_mask:0xf
	v_mov_b32_dpp v45, v129 row_shr:1 row_mask:0xf bank_mask:0xf
	v_pk_fma_f32 v[46:47], v[112:113], v[46:47], v[160:161]
	v_pk_fma_f32 v[6:7], v[130:131], v[92:93], v[6:7]
	v_pk_fma_f32 v[10:11], v[96:97], v[44:45], v[46:47]
	v_mul_f32_e32 v46, 0xbfb8aa3b, v6
	s_setprio 0
	v_exp_f32_e32 v46, v46
	v_mov_b32_e32 v18, v2
	v_mov_b32_e32 v19, v2
	v_mov_b32_e32 v50, v2
	v_mov_b32_e32 v51, v2
	v_mov_b32_e32 v14, v2
	v_mov_b32_dpp v18, v116 row_shr:2 row_mask:0xf bank_mask:0xf
	v_mov_b32_e32 v15, v2
	v_mov_b32_dpp v19, v117 row_shr:2 row_mask:0xf bank_mask:0xf
	v_mov_b32_e32 v48, v2
	v_mov_b32_dpp v50, v118 row_shr:2 row_mask:0xf bank_mask:0xf
	v_mov_b32_e32 v49, v2
	v_mov_b32_dpp v51, v119 row_shr:2 row_mask:0xf bank_mask:0xf
	v_mov_b32_dpp v14, v116 row_shr:1 row_mask:0xf bank_mask:0xf
	v_mov_b32_dpp v15, v117 row_shr:1 row_mask:0xf bank_mask:0xf
	v_mov_b32_dpp v48, v118 row_shr:1 row_mask:0xf bank_mask:0xf
	v_mov_b32_dpp v49, v119 row_shr:1 row_mask:0xf bank_mask:0xf
	v_pk_fma_f32 v[44:45], v[98:99], v[50:51], v[106:107]
	v_pk_fma_f32 v[18:19], v[94:95], v[18:19], v[102:103]
	v_pk_fma_f32 v[10:11], v[128:129], v[104:105], v[10:11]
	v_pk_fma_f32 v[14:15], v[86:87], v[14:15], v[18:19]
	v_pk_fma_f32 v[18:19], v[88:89], v[48:49], v[44:45]
	v_add_f32_e32 v44, 1.0, v46
	v_rcp_f32_e32 v44, v44
	v_mul_f32_e32 v45, 0xbfb8aa3b, v7
	v_exp_f32_e32 v45, v45
	v_pk_fma_f32 v[14:15], v[116:117], v[84:85], v[14:15]
	v_mul_f32_e32 v6, v6, v44
	v_mul_f32_e32 v6, v14, v6
	v_add_f32_e32 v14, 1.0, v45
	v_mul_f32_e32 v44, 0xbfb8aa3b, v10
	v_mul_f32_e32 v45, 0xbfb8aa3b, v11
	v_rcp_f32_e32 v14, v14
	v_exp_f32_e32 v44, v44
	v_exp_f32_e32 v45, v45
	v_mov_b32_dpp v38, v130 row_ror:2 row_mask:0xf bank_mask:0xf bound_ctrl:1
	v_mul_f32_e32 v7, v7, v14
	v_add_f32_e32 v14, 1.0, v44
	v_add_f32_e32 v44, 1.0, v45
	v_rcp_f32_e32 v14, v14
	v_rcp_f32_e32 v44, v44
	v_mov_b32_dpp v39, v131 row_ror:2 row_mask:0xf bank_mask:0xf bound_ctrl:1
	s_setprio 1
	v_mov_b32_dpp v54, v128 row_ror:2 row_mask:0xf bank_mask:0xf bound_ctrl:1
	v_mov_b32_dpp v55, v129 row_ror:2 row_mask:0xf bank_mask:0xf bound_ctrl:1
	v_pk_fma_f32 v[18:19], v[118:119], v[90:91], v[18:19]
	v_mul_f32_e32 v10, v10, v14
	v_mul_f32_e32 v11, v11, v44
	v_mov_b32_dpp v36, v130 row_ror:1 row_mask:0xf bank_mask:0xf bound_ctrl:1
	v_mov_b32_dpp v37, v131 row_ror:1 row_mask:0xf bank_mask:0xf bound_ctrl:1
	v_mov_b32_dpp v52, v128 row_ror:1 row_mask:0xf bank_mask:0xf bound_ctrl:1
	v_mov_b32_dpp v53, v129 row_ror:1 row_mask:0xf bank_mask:0xf bound_ctrl:1
	v_mul_f32_e32 v7, v15, v7
	v_mul_f32_e32 v10, v18, v10
	v_mul_f32_e32 v11, v19, v11
	v_mov_b32_dpp v38, v34 row_shr:2 row_mask:0xf bank_mask:0xf
	v_mov_b32_dpp v39, v35 row_shr:2 row_mask:0xf bank_mask:0xf
	v_mov_b32_dpp v54, v32 row_shr:2 row_mask:0xf bank_mask:0xf
	v_mov_b32_dpp v55, v33 row_shr:2 row_mask:0xf bank_mask:0xf
; __device__ __forceinline__ unsigned cvt_pk_bf16(float lo, float hi) { unsigned r; asm volatile("v_cvt_pk_bf16_f32 %0, %1, %2" : "=v"(r) : "v"(lo), "v"(hi)); return r; }
; __device__ __forceinline__ float fexp2(float x) { return __builtin_amdgcn_exp2f(x); }
; __device__ __forceinline__ float frcp(float x) { return __builtin_amdgcn_rcpf(x); }
; __device__ __forceinline__ float dpp_shr1(float old, float src) { return __int_as_float(__builtin_amdgcn_update_dpp(__float_as_int(old), __float_as_int(src), 0x111, 0xf, 0xf, false)); }
; __device__ __forceinline__ float dpp_shr2(float old, float src) { return __int_as_float(__builtin_amdgcn_update_dpp(__float_as_int(old), __float_as_int(src), 0x112, 0xf, 0xf, false)); }
; __device__ __forceinline__ float dpp_ror1(float src) { return __int_as_float(__builtin_amdgcn_mov_dpp(__float_as_int(src), 0x121, 0xf, 0xf, true)); }
; __device__ __forceinline__ float dpp_ror2(float src) { return __int_as_float(__builtin_amdgcn_mov_dpp(__float_as_int(src), 0x122, 0xf, 0xf, true)); }
;     __device__ __forceinline__ void operator()(f32x4 (&acc)[2][2][4][2], const Unit& u, int wr, int wc, int fr, int fq) const {
;     ...
;                 for (int m = 0; m < 4; ++m) {
;                     const f32x4 zg = acc[ai][0][m][n], zv = acc[ai][1][m][n];
;                     f32x4 g1, g2, v1, v2;
; #pragma unroll
;                     for (int j = 0; j < 4; ++j) { g1[j] = dpp_shr1(pg1[j], zg[j]); g2[j] = dpp_shr2(pg2[j], zg[j]); v1[j] = dpp_shr1(pv1[j], zv[j]); v2[j] = dpp_shr2(pv2[j], zv[j]);
;                         pg1[j] = dpp_ror1(zg[j]); pg2[j] = dpp_ror2(zg[j]); pv1[j] = dpp_ror1(zv[j]); pv2[j] = dpp_ror2(zv[j]); }
;                     const f32x4 cg_ = bg + wg0 * g2 + wg1 * g1 + wg2 * zg, cv_ = bv + wv0 * v2 + wv1 * v1 + wv2 * zv;
;                     float o[4];
; #pragma unroll
;                     for (int j = 0; j < 4; ++j) o[j] = cg_[j] * frcp(1.0f + fexp2(-1.4426950409f * cg_[j])) * cv_[j];
;                     pk[m][n][0] = cvt_pk_bf16(o[0], o[1]); pk[m][n][1] = cvt_pk_bf16(o[2], o[3]);
	v_cvt_pk_bf16_f32 v6, v6, v7
	v_cvt_pk_bf16_f32 v7, v10, v11
	v_mov_b32_dpp v36, v34 row_shr:1 row_mask:0xf bank_mask:0xf
	v_mov_b32_dpp v37, v35 row_shr:1 row_mask:0xf bank_mask:0xf
	v_mov_b32_dpp v52, v32 row_shr:1 row_mask:0xf bank_mask:0xf
	v_mov_b32_dpp v53, v33 row_shr:1 row_mask:0xf bank_mask:0xf
	v_pk_fma_f32 v[10:11], v[112:113], v[54:55], v[160:161]
	v_pk_fma_f32 v[38:39], v[100:101], v[38:39], v[150:151]
	v_pk_fma_f32 v[10:11], v[96:97], v[52:53], v[10:11]
	v_pk_fma_f32 v[36:37], v[108:109], v[36:37], v[38:39]
	v_mov_b32_dpp v48, v32 row_ror:1 row_mask:0xf bank_mask:0xf bound_ctrl:1
	v_mov_b32_dpp v50, v32 row_ror:2 row_mask:0xf bank_mask:0xf bound_ctrl:1
	v_mov_b32_dpp v49, v33 row_ror:1 row_mask:0xf bank_mask:0xf bound_ctrl:1
	v_mov_b32_dpp v51, v33 row_ror:2 row_mask:0xf bank_mask:0xf bound_ctrl:1
	v_pk_fma_f32 v[10:11], v[32:33], v[104:105], v[10:11]
	v_pk_fma_f32 v[32:33], v[34:35], v[92:93], v[36:37]
	v_mov_b32_dpp v58, v118 row_ror:2 row_mask:0xf bank_mask:0xf bound_ctrl:1
	v_mul_f32_e32 v38, 0xbfb8aa3b, v32
	v_mov_b32_dpp v59, v119 row_ror:2 row_mask:0xf bank_mask:0xf bound_ctrl:1
	v_exp_f32_e32 v38, v38
	v_mov_b32_dpp v56, v118 row_ror:1 row_mask:0xf bank_mask:0xf bound_ctrl:1
	v_mov_b32_dpp v57, v119 row_ror:1 row_mask:0xf bank_mask:0xf bound_ctrl:1
	s_setprio 0
	v_mov_b32_dpp v58, v30 row_shr:2 row_mask:0xf bank_mask:0xf
	v_mov_b32_dpp v59, v31 row_shr:2 row_mask:0xf bank_mask:0xf
	v_mov_b32_dpp v14, v34 row_ror:1 row_mask:0xf bank_mask:0xf bound_ctrl:1
	v_mov_b32_dpp v18, v34 row_ror:2 row_mask:0xf bank_mask:0xf bound_ctrl:1
	v_mov_b32_dpp v15, v35 row_ror:1 row_mask:0xf bank_mask:0xf bound_ctrl:1
	v_mov_b32_dpp v19, v35 row_ror:2 row_mask:0xf bank_mask:0xf bound_ctrl:1
	v_mov_b32_dpp v56, v30 row_shr:1 row_mask:0xf bank_mask:0xf
	v_mov_b32_dpp v57, v31 row_shr:1 row_mask:0xf bank_mask:0xf
	v_pk_fma_f32 v[34:35], v[98:99], v[58:59], v[106:107]
	v_mov_b32_dpp v60, v30 row_ror:1 row_mask:0xf bank_mask:0xf bound_ctrl:1
	v_pk_fma_f32 v[34:35], v[88:89], v[56:57], v[34:35]
	v_mov_b32_dpp v62, v30 row_ror:2 row_mask:0xf bank_mask:0xf bound_ctrl:1
	v_mov_b32_dpp v61, v31 row_ror:1 row_mask:0xf bank_mask:0xf bound_ctrl:1
	v_mov_b32_dpp v63, v31 row_ror:2 row_mask:0xf bank_mask:0xf bound_ctrl:1
	v_pk_fma_f32 v[30:31], v[30:31], v[90:91], v[34:35]
	v_add_f32_e32 v34, 1.0, v38
	v_mov_b32_dpp v42, v116 row_ror:2 row_mask:0xf bank_mask:0xf bound_ctrl:1
	v_mov_b32_dpp v43, v117 row_ror:2 row_mask:0xf bank_mask:0xf bound_ctrl:1
	v_rcp_f32_e32 v34, v34
	v_mul_f32_e32 v35, 0xbfb8aa3b, v33
	v_mov_b32_dpp v40, v116 row_ror:1 row_mask:0xf bank_mask:0xf bound_ctrl:1
	v_mov_b32_dpp v41, v117 row_ror:1 row_mask:0xf bank_mask:0xf bound_ctrl:1
	v_mov_b32_dpp v42, v28 row_shr:2 row_mask:0xf bank_mask:0xf
	v_mov_b32_dpp v43, v29 row_shr:2 row_mask:0xf bank_mask:0xf
	v_exp_f32_e32 v35, v35
	v_mov_b32_dpp v40, v28 row_shr:1 row_mask:0xf bank_mask:0xf
	v_mov_b32_dpp v41, v29 row_shr:1 row_mask:0xf bank_mask:0xf
	v_pk_fma_f32 v[36:37], v[94:95], v[42:43], v[102:103]
	v_mov_b32_dpp v44, v28 row_ror:1 row_mask:0xf bank_mask:0xf bound_ctrl:1
	v_pk_fma_f32 v[36:37], v[86:87], v[40:41], v[36:37]
	v_mov_b32_dpp v46, v28 row_ror:2 row_mask:0xf bank_mask:0xf bound_ctrl:1
	v_mov_b32_dpp v45, v29 row_ror:1 row_mask:0xf bank_mask:0xf bound_ctrl:1
	v_mov_b32_dpp v47, v29 row_ror:2 row_mask:0xf bank_mask:0xf bound_ctrl:1
	v_pk_fma_f32 v[28:29], v[28:29], v[84:85], v[36:37]
	v_mul_f32_e32 v32, v32, v34
	v_mul_f32_e32 v28, v28, v32
	v_add_f32_e32 v32, 1.0, v35
	v_mul_f32_e32 v34, 0xbfb8aa3b, v10
	v_rcp_f32_e32 v32, v32
	v_exp_f32_e32 v34, v34
	v_mul_f32_e32 v35, 0xbfb8aa3b, v11
	v_exp_f32_e32 v35, v35
	s_setprio 1
	v_mul_f32_e32 v32, v33, v32
	v_add_f32_e32 v33, 1.0, v34
	v_rcp_f32_e32 v33, v33
	v_add_f32_e32 v34, 1.0, v35
	v_rcp_f32_e32 v34, v34
	v_mov_b32_dpp v18, v26 row_shr:2 row_mask:0xf bank_mask:0xf
	v_mov_b32_dpp v19, v27 row_shr:2 row_mask:0xf bank_mask:0xf
	v_mul_f32_e32 v10, v10, v33
	v_mov_b32_dpp v14, v26 row_shr:1 row_mask:0xf bank_mask:0xf
	v_mov_b32_dpp v15, v27 row_shr:1 row_mask:0xf bank_mask:0xf
	v_pk_fma_f32 v[18:19], v[100:101], v[18:19], v[150:151]
	v_mul_f32_e32 v30, v30, v10
	v_mul_f32_e32 v10, v11, v34
	v_pk_fma_f32 v[14:15], v[108:109], v[14:15], v[18:19]
	v_mul_f32_e32 v29, v29, v32
	v_mul_f32_e32 v11, v31, v10
	v_mov_b32_dpp v46, v20 row_shr:2 row_mask:0xf bank_mask:0xf
	v_mov_b32_dpp v47, v21 row_shr:2 row_mask:0xf bank_mask:0xf
	v_pk_fma_f32 v[14:15], v[26:27], v[92:93], v[14:15]
	v_cvt_pk_bf16_f32 v10, v28, v29
	v_cvt_pk_bf16_f32 v11, v30, v11
	v_mov_b32_dpp v28, v26 row_ror:1 row_mask:0xf bank_mask:0xf bound_ctrl:1
	v_mov_b32_dpp v30, v26 row_ror:2 row_mask:0xf bank_mask:0xf bound_ctrl:1
	v_mov_b32_dpp v29, v27 row_ror:1 row_mask:0xf bank_mask:0xf bound_ctrl:1
	v_mov_b32_dpp v31, v27 row_ror:2 row_mask:0xf bank_mask:0xf bound_ctrl:1
	v_mov_b32_dpp v50, v24 row_shr:2 row_mask:0xf bank_mask:0xf
	v_mov_b32_dpp v51, v25 row_shr:2 row_mask:0xf bank_mask:0xf
	v_pk_fma_f32 v[26:27], v[94:95], v[46:47], v[102:103]
	v_mul_f32_e32 v46, 0xbfb8aa3b, v14
	v_mov_b32_dpp v48, v24 row_shr:1 row_mask:0xf bank_mask:0xf
	v_mov_b32_dpp v49, v25 row_shr:1 row_mask:0xf bank_mask:0xf
	v_pk_fma_f32 v[50:51], v[112:113], v[50:51], v[160:161]
	v_exp_f32_e32 v46, v46
	v_mov_b32_dpp v62, v22 row_shr:2 row_mask:0xf bank_mask:0xf
	v_mov_b32_dpp v63, v23 row_shr:2 row_mask:0xf bank_mask:0xf
	v_pk_fma_f32 v[18:19], v[96:97], v[48:49], v[50:51]
	v_mov_b32_dpp v60, v22 row_shr:1 row_mask:0xf bank_mask:0xf
; __device__ __forceinline__ unsigned cvt_pk_bf16(float lo, float hi) { unsigned r; asm volatile("v_cvt_pk_bf16_f32 %0, %1, %2" : "=v"(r) : "v"(lo), "v"(hi)); return r; }
; __device__ __forceinline__ float fexp2(float x) { return __builtin_amdgcn_exp2f(x); }
; __device__ __forceinline__ float frcp(float x) { return __builtin_amdgcn_rcpf(x); }
; #define PG8_BAR __builtin_amdgcn_s_barrier()
;     __device__ __forceinline__ void operator()(f32x4 (&acc)[2][2][4][2], const Unit& u, int wr, int wc, int fr, int fq) const {
;     ...
;                 for (int m = 0; m < 4; ++m) {
;                     const f32x4 zg = acc[ai][0][m][n], zv = acc[ai][1][m][n];
;                     f32x4 g1, g2, v1, v2;
; #pragma unroll
;                     for (int j = 0; j < 4; ++j) { g1[j] = dpp_shr1(pg1[j], zg[j]); g2[j] = dpp_shr2(pg2[j], zg[j]); v1[j] = dpp_shr1(pv1[j], zv[j]); v2[j] = dpp_shr2(pv2[j], zv[j]);
;                         pg1[j] = dpp_ror1(zg[j]); pg2[j] = dpp_ror2(zg[j]); pv1[j] = dpp_ror1(zv[j]); pv2[j] = dpp_ror2(zv[j]); }
;                     const f32x4 cg_ = bg + wg0 * g2 + wg1 * g1 + wg2 * zg, cv_ = bv + wv0 * v2 + wv1 * v1 + wv2 * zv;
;                     float o[4];
; #pragma unroll
;                     for (int j = 0; j < 4; ++j) o[j] = cg_[j] * frcp(1.0f + fexp2(-1.4426950409f * cg_[j])) * cv_[j];
;                     pk[m][n][0] = cvt_pk_bf16(o[0], o[1]); pk[m][n][1] = cvt_pk_bf16(o[2], o[3]);
;                 }
;             }
; #pragma unroll
;             for (int m = 0; m < 4; ++m) { u32x4 w; w.x = pk[m][0][0]; w.y = pk[m][0][1]; w.z = pk[m][1][0]; w.w = pk[m][1][1];
;                 *(u32x4*)(act + (size_t)(row0 + ai * HALF + m * 16) * 2816 + f0) = w; }
; template <class Epi, class Sched, bool ALIGN_EPI = false, bool SP2 = false>
; __device__ __forceinline__ void gemm_phase(PG8_LAS unsigned char* lds, const Gemm g, const Sched& S, const Epi& E, const int tid) {
;     ...
;         if (!has_next) break;
; #pragma unroll
;         for (int a = 0; a < 2; ++a)
; #pragma unroll
;             for (int b = 0; b < 2; ++b)
; #pragma unroll
;                 for (int m = 0; m < 4; ++m)
; #pragma unroll
;                     for (int n = 0; n < 2; ++n) acc[a][b][m][n] = (f32x4){0.f, 0.f, 0.f, 0.f};
;         cur = nxt; cA = nA; cB = nB; ++ui;
;         if constexpr (ALIGN_EPI) { if (wr == 1) PG8_BAR; }
	v_mov_b32_dpp v36, v24 row_ror:1 row_mask:0xf bank_mask:0xf bound_ctrl:1
	s_setprio 0
	v_mov_b32_dpp v38, v24 row_ror:2 row_mask:0xf bank_mask:0xf bound_ctrl:1
	v_mov_b32_dpp v61, v23 row_shr:1 row_mask:0xf bank_mask:0xf
	v_mov_b32_dpp v37, v25 row_ror:1 row_mask:0xf bank_mask:0xf bound_ctrl:1
	v_mov_b32_dpp v39, v25 row_ror:2 row_mask:0xf bank_mask:0xf bound_ctrl:1
	v_pk_fma_f32 v[18:19], v[24:25], v[104:105], v[18:19]
	v_pk_fma_f32 v[24:25], v[98:99], v[62:63], v[106:107]
	v_mov_b32_dpp v40, v22 row_ror:1 row_mask:0xf bank_mask:0xf bound_ctrl:1
	v_pk_fma_f32 v[24:25], v[88:89], v[60:61], v[24:25]
	v_mov_b32_dpp v42, v22 row_ror:2 row_mask:0xf bank_mask:0xf bound_ctrl:1
	v_mov_b32_dpp v41, v23 row_ror:1 row_mask:0xf bank_mask:0xf bound_ctrl:1
	v_mov_b32_dpp v43, v23 row_ror:2 row_mask:0xf bank_mask:0xf bound_ctrl:1
	v_pk_fma_f32 v[22:23], v[22:23], v[90:91], v[24:25]
	v_add_f32_e32 v24, 1.0, v46
	v_rcp_f32_e32 v24, v24
	v_mul_f32_e32 v25, 0xbfb8aa3b, v15
	v_exp_f32_e32 v25, v25
	v_mov_b32_dpp v44, v20 row_shr:1 row_mask:0xf bank_mask:0xf
	v_mov_b32_dpp v45, v21 row_shr:1 row_mask:0xf bank_mask:0xf
	v_pk_fma_f32 v[26:27], v[86:87], v[44:45], v[26:27]
	v_mov_b32_dpp v32, v20 row_ror:1 row_mask:0xf bank_mask:0xf bound_ctrl:1
	v_mov_b32_dpp v34, v20 row_ror:2 row_mask:0xf bank_mask:0xf bound_ctrl:1
	v_mov_b32_dpp v33, v21 row_ror:1 row_mask:0xf bank_mask:0xf bound_ctrl:1
	v_mov_b32_dpp v35, v21 row_ror:2 row_mask:0xf bank_mask:0xf bound_ctrl:1
	v_pk_fma_f32 v[20:21], v[20:21], v[84:85], v[26:27]
	v_mul_f32_e32 v14, v14, v24
	v_mul_f32_e32 v14, v20, v14
	v_add_f32_e32 v20, 1.0, v25
	v_mul_f32_e32 v24, 0xbfb8aa3b, v18
	v_rcp_f32_e32 v20, v20
	v_exp_f32_e32 v24, v24
	v_mul_f32_e32 v25, 0xbfb8aa3b, v19
	v_mov_b32_dpp v30, v80 row_shr:2 row_mask:0xf bank_mask:0xf
	v_mul_f32_e32 v15, v15, v20
	v_add_f32_e32 v20, 1.0, v24
	v_rcp_f32_e32 v20, v20
	v_mov_b32_dpp v31, v81 row_shr:2 row_mask:0xf bank_mask:0xf
	v_exp_f32_e32 v25, v25
	v_mul_f32_e32 v15, v21, v15
	v_mul_f32_e32 v18, v18, v20
	v_mov_b32_dpp v28, v80 row_shr:1 row_mask:0xf bank_mask:0xf
	v_mov_b32_dpp v29, v81 row_shr:1 row_mask:0xf bank_mask:0xf
	v_pk_fma_f32 v[20:21], v[100:101], v[30:31], v[150:151]
	s_setprio 1
	v_add_f32_e32 v24, 1.0, v25
	v_pk_fma_f32 v[20:21], v[108:109], v[28:29], v[20:21]
	v_rcp_f32_e32 v24, v24
	v_pk_fma_f32 v[20:21], v[80:81], v[92:93], v[20:21]
	v_mul_f32_e32 v18, v22, v18
	v_mul_f32_e32 v26, 0xbfb8aa3b, v20
	v_exp_f32_e32 v26, v26
	v_mul_f32_e32 v19, v19, v24
	v_mul_f32_e32 v27, 0xbfb8aa3b, v21
	v_mul_f32_e32 v19, v23, v19
	v_add_f32_e32 v26, 1.0, v26
	v_rcp_f32_e32 v26, v26
	v_mov_b32_dpp v34, v70 row_shr:2 row_mask:0xf bank_mask:0xf
	v_mov_b32_dpp v35, v71 row_shr:2 row_mask:0xf bank_mask:0xf
	v_mov_b32_dpp v38, v74 row_shr:2 row_mask:0xf bank_mask:0xf
	v_mov_b32_dpp v39, v75 row_shr:2 row_mask:0xf bank_mask:0xf
	v_exp_f32_e32 v27, v27
	v_cvt_pk_bf16_f32 v14, v14, v15
	v_cvt_pk_bf16_f32 v15, v18, v19
	v_mov_b32_dpp v32, v70 row_shr:1 row_mask:0xf bank_mask:0xf
	v_mov_b32_dpp v33, v71 row_shr:1 row_mask:0xf bank_mask:0xf
	v_mov_b32_dpp v36, v74 row_shr:1 row_mask:0xf bank_mask:0xf
	v_mov_b32_dpp v37, v75 row_shr:1 row_mask:0xf bank_mask:0xf
	v_pk_fma_f32 v[18:19], v[112:113], v[38:39], v[160:161]
	v_pk_fma_f32 v[24:25], v[94:95], v[34:35], v[102:103]
	v_pk_fma_f32 v[18:19], v[96:97], v[36:37], v[18:19]
	v_pk_fma_f32 v[24:25], v[86:87], v[32:33], v[24:25]
	v_pk_fma_f32 v[18:19], v[74:75], v[104:105], v[18:19]
	v_pk_fma_f32 v[24:25], v[70:71], v[84:85], v[24:25]
	v_mul_f32_e32 v20, v20, v26
	v_mul_f32_e32 v20, v24, v20
	v_add_f32_e32 v24, 1.0, v27
	v_mul_f32_e32 v26, 0xbfb8aa3b, v18
	v_rcp_f32_e32 v24, v24
	v_exp_f32_e32 v26, v26
	v_mul_f32_e32 v27, 0xbfb8aa3b, v19
	v_exp_f32_e32 v27, v27
	v_mul_f32_e32 v21, v21, v24
	v_add_f32_e32 v24, 1.0, v26
	v_rcp_f32_e32 v24, v24
	v_add_f32_e32 v26, 1.0, v27
	v_mov_b32_dpp v42, v72 row_shr:2 row_mask:0xf bank_mask:0xf
	v_mov_b32_dpp v43, v73 row_shr:2 row_mask:0xf bank_mask:0xf
	v_rcp_f32_e32 v26, v26
	v_mov_b32_dpp v40, v72 row_shr:1 row_mask:0xf bank_mask:0xf
	v_mov_b32_dpp v41, v73 row_shr:1 row_mask:0xf bank_mask:0xf
	v_pk_fma_f32 v[22:23], v[98:99], v[42:43], v[106:107]
	v_mul_f32_e32 v18, v18, v24
	v_pk_fma_f32 v[22:23], v[88:89], v[40:41], v[22:23]
	v_mul_f32_e32 v21, v25, v21
	v_pk_fma_f32 v[22:23], v[72:73], v[90:91], v[22:23]
	v_add_u32_e32 v177, 0x90, v176
	v_mul_f32_e32 v22, v22, v18
	v_mul_f32_e32 v18, v19, v26
	v_mul_f32_e32 v19, v23, v18
	s_setprio 0
	v_cvt_pk_bf16_f32 v18, v20, v21
	v_mad_i64_i32 v[20:21], s[18:19], v246, s22, v[110:111]
	v_lshl_add_u64 v[20:21], v[20:21], 0, v[68:69]
	v_cvt_pk_bf16_f32 v19, v22, v19
	global_store_dwordx4 v[20:21], v[4:7], off
	v_add_u32_e32 v247, 0xa0, v176
	v_add_u32_e32 v248, 0xb0, v176
	v_mad_i64_i32 v[4:5], s[18:19], v177, s22, v[110:111]
	v_lshl_add_u64 v[4:5], v[4:5], 0, v[68:69]
	global_store_dwordx4 v[4:5], v[8:11], off
	v_mad_i64_i32 v[4:5], s[18:19], v247, s22, v[110:111]
	v_lshl_add_u64 v[4:5], v[4:5], 0, v[68:69]
	global_store_dwordx4 v[4:5], v[12:15], off
	v_mad_i64_i32 v[4:5], s[18:19], v248, s22, v[110:111]
	v_lshl_add_u64 v[4:5], v[4:5], 0, v[68:69]
	global_store_dwordx4 v[4:5], v[16:19], off
	v_readlane_b32 s46, v254, 53
	s_andn2_b64 vcc, exec, s[42:43]
	s_mov_b64 s[18:19], -1
	v_readlane_b32 s47, v254, 54
	s_cbranch_vccnz .LBB0_31
	v_readlane_b32 s18, v252, 2
	v_readlane_b32 s19, v252, 3
	s_andn2_b64 vcc, exec, s[18:19]
	s_cbranch_vccnz .LBB0_30
	s_barrier
	s_branch .LBB0_30
